# softmax max chain: drop fmaxf canonicalising v_max x,x (54 VALU ops -> s_nop 0 in place, same bytes)
# speedup vs baseline: 1.0035x; 1.0035x over previous
.Lmpp_a_sJ:
	s_nop 1
	s_nop 0
	s_nop 0
	v_max_f32_e32 v191, v83, v82
	v_max3_f32 v191, v191, v84, v85
	v_max3_f32 v191, v191, v86, v87
	v_max3_f32 v191, v191, v88, v89
	v_max3_f32 v191, v191, v90, v91
	v_max3_f32 v191, v191, v92, v93
	v_max3_f32 v191, v191, v94, v95
	v_max3_f32 v191, v191, v96, v97
	v_max3_f32 v191, v191, v66, v67
	v_max3_f32 v191, v191, v68, v69
	v_max3_f32 v191, v191, v70, v71
	v_max3_f32 v191, v191, v72, v73
	v_max3_f32 v191, v191, v74, v75
	v_max3_f32 v191, v191, v76, v77
	v_max3_f32 v191, v191, v78, v79
	v_max3_f32 v191, v191, v80, v81
	v_mov_b32_e32 v235, v191
	s_nop 1
	v_permlane32_swap_b32_e32 v191, v235
	s_nop 0
	s_nop 0
	v_max_f32_e32 v191, v235, v191
	v_sub_f32_e32 v235, v191, v189
	v_cmp_ge_f32_e32 vcc, s56, v235
	s_cmp_eq_u64 vcc, exec
	s_nop 0
	s_cselect_b64 vcc, -1, 0
	v_max_f32_e32 v191, v189, v191
	v_sub_f32_e32 v235, v189, v191
	v_cndmask_b32_e32 v189, v191, v189, vcc
	v_mul_f32_e32 v191, 0xbdd53b94, v189
	v_fmamk_f32 v82, v82, 0x3dd53b94, v191
	v_fmamk_f32 v83, v83, 0x3dd53b94, v191
	v_fmamk_f32 v84, v84, 0x3dd53b94, v191
	v_fmamk_f32 v85, v85, 0x3dd53b94, v191
	v_fmamk_f32 v86, v86, 0x3dd53b94, v191
	v_fmamk_f32 v87, v87, 0x3dd53b94, v191
	v_fmamk_f32 v88, v88, 0x3dd53b94, v191
	v_fmamk_f32 v89, v89, 0x3dd53b94, v191
	v_fmamk_f32 v90, v90, 0x3dd53b94, v191
	v_fmamk_f32 v91, v91, 0x3dd53b94, v191
	v_fmamk_f32 v92, v92, 0x3dd53b94, v191
	v_fmamk_f32 v93, v93, 0x3dd53b94, v191
	v_fmamk_f32 v94, v94, 0x3dd53b94, v191
	v_fmamk_f32 v95, v95, 0x3dd53b94, v191
	v_fmamk_f32 v96, v96, 0x3dd53b94, v191
	v_fmamk_f32 v97, v97, 0x3dd53b94, v191
	v_fmamk_f32 v66, v66, 0x3dd53b94, v191
	v_fmamk_f32 v67, v67, 0x3dd53b94, v191
	v_fmamk_f32 v68, v68, 0x3dd53b94, v191
	v_fmamk_f32 v69, v69, 0x3dd53b94, v191
	v_fmamk_f32 v70, v70, 0x3dd53b94, v191
	v_fmamk_f32 v71, v71, 0x3dd53b94, v191
	v_fmamk_f32 v72, v72, 0x3dd53b94, v191
	v_fmamk_f32 v73, v73, 0x3dd53b94, v191
	v_fmamk_f32 v74, v74, 0x3dd53b94, v191
	v_fmamk_f32 v75, v75, 0x3dd53b94, v191
	v_fmamk_f32 v76, v76, 0x3dd53b94, v191
	v_fmamk_f32 v77, v77, 0x3dd53b94, v191
	v_fmamk_f32 v78, v78, 0x3dd53b94, v191
	v_fmamk_f32 v79, v79, 0x3dd53b94, v191
	v_fmamk_f32 v80, v80, 0x3dd53b94, v191
	v_fmac_f32_e32 v191, 0x3dd53b94, v81
	v_exp_f32_e32 v81, v82
	v_exp_f32_e32 v236, v83
	v_exp_f32_e32 v84, v84
	v_exp_f32_e32 v85, v85
	v_exp_f32_e32 v86, v86
	v_exp_f32_e32 v237, v70
	v_add_f32_e32 v70, 0, v81
	v_exp_f32_e32 v87, v87
	v_add_f32_e32 v70, v236, v70
	v_exp_f32_e32 v88, v88
	v_add_f32_e32 v70, v84, v70
	v_exp_f32_e32 v89, v89
	v_add_f32_e32 v70, v85, v70
	v_exp_f32_e32 v90, v90
	v_add_f32_e32 v70, v86, v70
	v_exp_f32_e32 v91, v91
	v_add_f32_e32 v70, v87, v70
	v_exp_f32_e32 v92, v92
	v_add_f32_e32 v70, v88, v70
	v_exp_f32_e32 v93, v93
	v_add_f32_e32 v70, v89, v70
	v_exp_f32_e32 v94, v94
	v_add_f32_e32 v70, v90, v70
	v_exp_f32_e32 v95, v95
	v_add_f32_e32 v70, v91, v70
	v_exp_f32_e32 v96, v96
	v_add_f32_e32 v70, v92, v70
	v_exp_f32_e32 v97, v97
	v_add_f32_e32 v70, v93, v70
	v_exp_f32_e32 v66, v66
	v_add_f32_e32 v70, v94, v70
	v_exp_f32_e32 v67, v67
	v_add_f32_e32 v70, v95, v70
	v_exp_f32_e32 v68, v68
	v_add_f32_e32 v70, v96, v70
	v_exp_f32_e32 v69, v69
	v_add_f32_e32 v70, v97, v70
	v_add_f32_e32 v70, v66, v70
	v_exp_f32_e32 v238, v71
	v_add_f32_e32 v70, v67, v70
	v_exp_f32_e32 v239, v72
	v_add_f32_e32 v70, v68, v70
	v_exp_f32_e32 v73, v73
	v_add_f32_e32 v70, v69, v70
	v_exp_f32_e32 v240, v74
	v_add_f32_e32 v70, v237, v70
	v_exp_f32_e32 v241, v75
	v_add_f32_e32 v70, v238, v70
	v_exp_f32_e32 v242, v76
	v_add_f32_e32 v70, v239, v70
	v_exp_f32_e32 v243, v77
	v_add_f32_e32 v70, v73, v70
	v_exp_f32_e32 v244, v78
	v_add_f32_e32 v70, v240, v70
	v_exp_f32_e32 v245, v79
	v_add_f32_e32 v70, v241, v70
	v_exp_f32_e32 v246, v80
	v_add_f32_e32 v70, v242, v70
	v_mul_f32_e32 v235, 0x3dd53b94, v235
	v_exp_f32_e32 v191, v191
	v_add_f32_e32 v70, v243, v70
	v_exp_f32_e32 v235, v235
	v_add_f32_e32 v70, v244, v70
	v_add_f32_e32 v70, v245, v70
	v_add_f32_e32 v70, v246, v70
	v_add_f32_e32 v82, v191, v70
	v_cndmask_b32_e64 v235, v235, 1.0, vcc
	v_mov_b32_e32 v83, v82
	s_nop 1
	v_permlane32_swap_b32_e32 v82, v83
	v_cmp_gt_f32_e32 vcc, 1.0, v235
	v_cvt_pk_bf16_f32 v78, v81, v236
	v_cvt_pk_bf16_f32 v79, v84, v85
	v_cvt_pk_bf16_f32 v80, v86, v87
	v_cvt_pk_bf16_f32 v81, v88, v89
	v_cvt_pk_bf16_f32 v74, v90, v91
	v_cvt_pk_bf16_f32 v75, v92, v93
	v_cvt_pk_bf16_f32 v76, v94, v95
	v_cvt_pk_bf16_f32 v77, v96, v97
	v_cvt_pk_bf16_f32 v70, v66, v67
	v_cvt_pk_bf16_f32 v71, v68, v69
	v_cvt_pk_bf16_f32 v72, v237, v238
	v_cvt_pk_bf16_f32 v73, v239, v73
	v_cvt_pk_bf16_f32 v66, v240, v241
	v_cvt_pk_bf16_f32 v67, v242, v243
	v_cvt_pk_bf16_f32 v68, v244, v245
	v_cvt_pk_bf16_f32 v69, v246, v191
	s_cbranch_vccz .Lmu_a124
	s_and_saveexec_b64 s[12:13], s[4:5]
	ds_write_b32 v232, v235 offset:128
	s_or_b64 exec, exec, s[12:13]
	s_waitcnt lgkmcnt(0)
	v_add_u32_e32 v96, v196, v202
	ds_read_b128 v[84:87], v96 offset:224
	ds_read_b128 v[88:91], v96 offset:192
	ds_read_b128 v[92:95], v96 offset:160
	ds_read_b128 v[236:239], v96 offset:128
	s_waitcnt lgkmcnt(3)
	v_pk_mul_f32 v[14:15], v[14:15], v[84:85]
	s_waitcnt lgkmcnt(2)
	v_pk_mul_f32 v[10:11], v[10:11], v[88:89]
	s_waitcnt lgkmcnt(1)
	v_pk_mul_f32 v[6:7], v[6:7], v[92:93]
	v_pk_mul_f32 v[16:17], v[16:17], v[86:87]
	v_pk_mul_f32 v[12:13], v[12:13], v[90:91]
	v_pk_mul_f32 v[8:9], v[8:9], v[94:95]
	s_waitcnt lgkmcnt(0)
	v_pk_mul_f32 v[4:5], v[4:5], v[238:239]
	v_pk_mul_f32 v[2:3], v[2:3], v[236:237]
	v_pk_mul_f32 v[30:31], v[30:31], v[84:85]
	v_pk_mul_f32 v[26:27], v[26:27], v[88:89]
	v_pk_mul_f32 v[22:23], v[22:23], v[92:93]
	v_pk_mul_f32 v[32:33], v[32:33], v[86:87]
	v_pk_mul_f32 v[28:29], v[28:29], v[90:91]
	v_pk_mul_f32 v[24:25], v[24:25], v[94:95]
	v_pk_mul_f32 v[20:21], v[20:21], v[238:239]
	v_pk_mul_f32 v[18:19], v[18:19], v[236:237]
	v_pk_mul_f32 v[46:47], v[46:47], v[84:85]
	v_pk_mul_f32 v[42:43], v[42:43], v[88:89]
	v_pk_mul_f32 v[38:39], v[38:39], v[92:93]
	v_pk_mul_f32 v[48:49], v[48:49], v[86:87]
	v_pk_mul_f32 v[44:45], v[44:45], v[90:91]
	v_pk_mul_f32 v[40:41], v[40:41], v[94:95]
	v_pk_mul_f32 v[36:37], v[36:37], v[238:239]
	v_pk_mul_f32 v[34:35], v[34:35], v[236:237]
	v_pk_mul_f32 v[62:63], v[62:63], v[84:85]
	v_pk_mul_f32 v[58:59], v[58:59], v[88:89]
	v_pk_mul_f32 v[54:55], v[54:55], v[92:93]
	v_pk_mul_f32 v[64:65], v[64:65], v[86:87]
	v_pk_mul_f32 v[60:61], v[60:61], v[90:91]
	v_pk_mul_f32 v[56:57], v[56:57], v[94:95]
	v_pk_mul_f32 v[52:53], v[52:53], v[238:239]
	v_pk_mul_f32 v[50:51], v[50:51], v[236:237]

.LBB0_126:
	s_mov_b32 s30, 0x13572468
	s_mov_b32 s30, 0x13572468
	s_mov_b32 s30, 0x13572468
	s_mov_b32 s30, 0x13572468
	s_mov_b32 s30, 0x13572468
	s_mov_b32 s30, 0x13572468
	s_mov_b32 s30, 0x13572468
	s_mov_b32 s30, 0x13572468
	s_mov_b32 s30, 0x13572468
	s_mov_b32 s30, 0x13572468
	s_mov_b32 s30, 0x13572468
	s_mov_b32 s30, 0x13572468
	s_mov_b32 s30, 0x13572468
	s_mov_b32 s30, 0x13572468
	s_mov_b32 s30, 0x13572468
	s_and_b32 s12, s22, 1
	s_mul_i32 s10, s12, 0x6000
	v_add_u32_e32 v150, s10, v203
	v_add_u32_e32 v70, v150, v220
	ds_read_b128 v[66:69], v70 offset:32768
	ds_read_b128 v[70:73], v70 offset:45056
	v_add_u32_e32 v146, v150, v221
	s_waitcnt lgkmcnt(1)
	v_mfma_f32_32x32x16_bf16 v[82:97], v[66:69], v[134:137], 0
	s_waitcnt lgkmcnt(0)
	v_mfma_f32_32x32x16_bf16 v[66:81], v[70:73], v[134:137], 0
	ds_read_b128 v[134:137], v146 offset:32768
	ds_read_b128 v[146:149], v146 offset:45056
	s_waitcnt lgkmcnt(1)
	v_mfma_f32_32x32x16_bf16 v[82:97], v[134:137], v[130:133], v[82:97]
	v_add_u32_e32 v134, v150, v222
	s_waitcnt lgkmcnt(0)
	v_mfma_f32_32x32x16_bf16 v[66:81], v[146:149], v[130:133], v[66:81]
	ds_read_b128 v[130:133], v134 offset:32768
	ds_read_b128 v[134:137], v134 offset:45056
	s_waitcnt lgkmcnt(1)
	v_mfma_f32_32x32x16_bf16 v[82:97], v[130:133], v[126:129], v[82:97]
	v_add_u32_e32 v130, v150, v223
	s_waitcnt lgkmcnt(0)
	v_mfma_f32_32x32x16_bf16 v[66:81], v[134:137], v[126:129], v[66:81]
	ds_read_b128 v[126:129], v130 offset:32768
	ds_read_b128 v[130:133], v130 offset:45056
	s_waitcnt lgkmcnt(1)
	v_mfma_f32_32x32x16_bf16 v[82:97], v[126:129], v[122:125], v[82:97]
	v_add_u32_e32 v126, v150, v224
	s_waitcnt lgkmcnt(0)
	v_mfma_f32_32x32x16_bf16 v[66:81], v[130:133], v[122:125], v[66:81]
	ds_read_b128 v[122:125], v126 offset:32768
	ds_read_b128 v[126:129], v126 offset:45056
	s_waitcnt lgkmcnt(1)
	v_mfma_f32_32x32x16_bf16 v[82:97], v[122:125], v[118:121], v[82:97]
	v_add_u32_e32 v122, v150, v225
	s_waitcnt lgkmcnt(0)
	v_mfma_f32_32x32x16_bf16 v[66:81], v[126:129], v[118:121], v[66:81]
	ds_read_b128 v[118:121], v122 offset:32768
	ds_read_b128 v[122:125], v122 offset:45056
	s_waitcnt lgkmcnt(1)
	v_mfma_f32_32x32x16_bf16 v[82:97], v[118:121], v[114:117], v[82:97]
	v_add_u32_e32 v118, v150, v226
	s_waitcnt lgkmcnt(0)
	v_mfma_f32_32x32x16_bf16 v[66:81], v[122:125], v[114:117], v[66:81]
	ds_read_b128 v[114:117], v118 offset:32768
	ds_read_b128 v[118:121], v118 offset:45056
	s_waitcnt lgkmcnt(1)
	v_mfma_f32_32x32x16_bf16 v[82:97], v[114:117], v[110:113], v[82:97]
	v_add_u32_e32 v114, v150, v227
	s_waitcnt lgkmcnt(0)
	v_mfma_f32_32x32x16_bf16 v[66:81], v[118:121], v[110:113], v[66:81]
	ds_read_b128 v[110:113], v114 offset:32768
	ds_read_b128 v[114:117], v114 offset:45056
	s_waitcnt lgkmcnt(1)
	v_mfma_f32_32x32x16_bf16 v[82:97], v[110:113], v[106:109], v[82:97]
	v_add_u32_e32 v110, v150, v228
	s_waitcnt lgkmcnt(0)
	v_mfma_f32_32x32x16_bf16 v[66:81], v[114:117], v[106:109], v[66:81]
	ds_read_b128 v[106:109], v110 offset:32768
	ds_read_b128 v[110:113], v110 offset:45056
	s_waitcnt lgkmcnt(1)
	v_mfma_f32_32x32x16_bf16 v[82:97], v[106:109], v[102:105], v[82:97]
	v_add_u32_e32 v106, v150, v229
	s_waitcnt lgkmcnt(0)
	v_mfma_f32_32x32x16_bf16 v[66:81], v[110:113], v[102:105], v[66:81]
	ds_read_b128 v[102:105], v106 offset:32768
	ds_read_b128 v[106:109], v106 offset:45056
	s_waitcnt lgkmcnt(1)
	v_mfma_f32_32x32x16_bf16 v[82:97], v[102:105], v[98:101], v[82:97]
	v_add_u32_e32 v102, v150, v230
	s_waitcnt lgkmcnt(0)
	v_mfma_f32_32x32x16_bf16 v[66:81], v[106:109], v[98:101], v[66:81]
	ds_read_b128 v[98:101], v102 offset:32768
	ds_read_b128 v[102:105], v102 offset:45056
	v_add_u32_e32 v106, v150, v231
	s_waitcnt lgkmcnt(1)
	v_mfma_f32_32x32x16_bf16 v[82:97], v[98:101], v[138:141], v[82:97]
	ds_read_b128 v[98:101], v106 offset:32768
	ds_read_b128 v[106:109], v106 offset:45056
	s_waitcnt lgkmcnt(1)
	v_mfma_f32_32x32x16_bf16 v[82:97], v[98:101], v[142:145], v[82:97]
	v_max_f32_e32 v100, v189, v189
	v_mfma_f32_32x32x16_bf16 v[66:81], v[102:105], v[138:141], v[66:81]
	s_nop 9
	s_nop 0
	s_nop 0
	v_max_f32_e32 v98, v83, v82
	v_max3_f32 v98, v98, v84, v85
	v_max3_f32 v98, v98, v86, v87
	v_max3_f32 v98, v98, v88, v89
	v_max3_f32 v98, v98, v90, v91
	s_waitcnt lgkmcnt(0)
	v_mfma_f32_32x32x16_bf16 v[66:81], v[106:109], v[142:145], v[66:81]
	v_max3_f32 v98, v98, v92, v93
	v_max3_f32 v98, v98, v94, v95
	v_max3_f32 v98, v98, v96, v97
	s_nop 8
	v_max3_f32 v98, v98, v66, v67
	v_max3_f32 v98, v98, v68, v69
	v_max3_f32 v98, v98, v70, v71
	v_max3_f32 v98, v98, v72, v73
	v_max3_f32 v98, v98, v74, v75
	v_max3_f32 v98, v98, v76, v77
	v_max3_f32 v98, v98, v78, v79
	v_max3_f32 v98, v98, v80, v81
	v_mov_b32_e32 v99, v98
	s_nop 1
	v_permlane32_swap_b32_e32 v98, v99
	s_nop 0
	s_nop 0
	v_max_f32_e32 v98, v99, v98
	v_sub_f32_e32 v99, v98, v189
	v_cmp_ge_f32_e32 vcc, s56, v99
	s_cmp_eq_u64 vcc, exec
	v_max_f32_e32 v100, v100, v98
	s_cselect_b64 vcc, -1, 0
	v_cndmask_b32_e32 v99, v100, v189, vcc
	v_mul_f32_e32 v99, 0xbdd53b94, v99
	v_fmamk_f32 v82, v82, 0x3dd53b94, v99
	v_fmamk_f32 v83, v83, 0x3dd53b94, v99
	v_fmamk_f32 v84, v84, 0x3dd53b94, v99
	v_fmamk_f32 v85, v85, 0x3dd53b94, v99
	v_fmamk_f32 v86, v86, 0x3dd53b94, v99
	v_fmamk_f32 v87, v87, 0x3dd53b94, v99
	v_fmamk_f32 v88, v88, 0x3dd53b94, v99
	v_fmamk_f32 v89, v89, 0x3dd53b94, v99
	v_fmamk_f32 v90, v90, 0x3dd53b94, v99
	v_fmamk_f32 v91, v91, 0x3dd53b94, v99
	v_fmamk_f32 v92, v92, 0x3dd53b94, v99
	v_fmamk_f32 v93, v93, 0x3dd53b94, v99
	v_fmamk_f32 v94, v94, 0x3dd53b94, v99
	v_fmamk_f32 v95, v95, 0x3dd53b94, v99
	v_fmamk_f32 v96, v96, 0x3dd53b94, v99
	v_fmamk_f32 v97, v97, 0x3dd53b94, v99
	v_fmamk_f32 v66, v66, 0x3dd53b94, v99
	v_fmamk_f32 v67, v67, 0x3dd53b94, v99
	v_fmamk_f32 v68, v68, 0x3dd53b94, v99
	v_fmamk_f32 v69, v69, 0x3dd53b94, v99
	v_fmamk_f32 v70, v70, 0x3dd53b94, v99
	v_fmamk_f32 v71, v71, 0x3dd53b94, v99
	v_fmamk_f32 v72, v72, 0x3dd53b94, v99
	v_fmamk_f32 v73, v73, 0x3dd53b94, v99
	v_fmamk_f32 v74, v74, 0x3dd53b94, v99
	v_fmamk_f32 v75, v75, 0x3dd53b94, v99
	v_fmamk_f32 v76, v76, 0x3dd53b94, v99
	v_fmamk_f32 v77, v77, 0x3dd53b94, v99
	v_fmamk_f32 v78, v78, 0x3dd53b94, v99
	v_fmamk_f32 v79, v79, 0x3dd53b94, v99
	v_fmamk_f32 v80, v80, 0x3dd53b94, v99
	v_fmac_f32_e32 v99, 0x3dd53b94, v81
	v_exp_f32_e32 v81, v82
	v_sub_f32_e32 v98, v189, v100
	v_exp_f32_e32 v100, v83
	v_exp_f32_e32 v84, v84
	v_exp_f32_e32 v85, v85
	v_exp_f32_e32 v86, v86
	v_exp_f32_e32 v101, v70
	v_add_f32_e32 v70, 0, v81
	v_exp_f32_e32 v87, v87
	v_add_f32_e32 v70, v100, v70
	v_exp_f32_e32 v88, v88
	v_add_f32_e32 v70, v84, v70
	v_exp_f32_e32 v89, v89
	v_add_f32_e32 v70, v85, v70
	v_exp_f32_e32 v90, v90
	v_add_f32_e32 v70, v86, v70
	v_exp_f32_e32 v91, v91
	v_add_f32_e32 v70, v87, v70
	v_exp_f32_e32 v92, v92
	v_add_f32_e32 v70, v88, v70
	v_exp_f32_e32 v93, v93
	v_add_f32_e32 v70, v89, v70
	v_exp_f32_e32 v94, v94
	v_add_f32_e32 v70, v90, v70
	v_exp_f32_e32 v95, v95
	v_add_f32_e32 v70, v91, v70
	v_exp_f32_e32 v96, v96
	v_add_f32_e32 v70, v92, v70
	v_exp_f32_e32 v97, v97
	v_add_f32_e32 v70, v93, v70
	v_exp_f32_e32 v66, v66
	v_add_f32_e32 v70, v94, v70
	v_exp_f32_e32 v67, v67
	v_add_f32_e32 v70, v95, v70
	v_exp_f32_e32 v68, v68
	v_add_f32_e32 v70, v96, v70
	v_exp_f32_e32 v69, v69
	v_add_f32_e32 v70, v97, v70
	v_add_f32_e32 v70, v66, v70
	v_exp_f32_e32 v102, v71
	v_add_f32_e32 v70, v67, v70
	v_exp_f32_e32 v103, v72
	v_add_f32_e32 v70, v68, v70
	v_exp_f32_e32 v73, v73
	v_add_f32_e32 v70, v69, v70
	v_exp_f32_e32 v104, v74
	v_add_f32_e32 v70, v101, v70
	v_exp_f32_e32 v105, v75
	v_add_f32_e32 v70, v102, v70
	v_exp_f32_e32 v106, v76
	v_add_f32_e32 v70, v103, v70
	v_exp_f32_e32 v107, v77
	v_add_f32_e32 v70, v73, v70
	v_exp_f32_e32 v108, v78
	v_add_f32_e32 v70, v104, v70
	v_exp_f32_e32 v109, v79
	v_add_f32_e32 v70, v105, v70
	v_exp_f32_e32 v110, v80
	v_add_f32_e32 v70, v106, v70
	v_mul_f32_e32 v98, 0x3dd53b94, v98
	v_exp_f32_e32 v99, v99
	v_add_f32_e32 v70, v107, v70
	v_exp_f32_e32 v98, v98
	v_add_f32_e32 v70, v108, v70
	v_add_f32_e32 v70, v109, v70
	v_add_f32_e32 v70, v110, v70
	v_add_f32_e32 v82, v99, v70
	v_cndmask_b32_e64 v98, v98, 1.0, vcc
	v_mov_b32_e32 v83, v82
	s_nop 1
	v_permlane32_swap_b32_e32 v82, v83
	v_cmp_gt_f32_e32 vcc, 1.0, v98
	v_cvt_pk_bf16_f32 v78, v81, v100
	v_cvt_pk_bf16_f32 v79, v84, v85
	v_cvt_pk_bf16_f32 v80, v86, v87
	v_cvt_pk_bf16_f32 v81, v88, v89
	v_cvt_pk_bf16_f32 v74, v90, v91
	v_cvt_pk_bf16_f32 v75, v92, v93
	v_cvt_pk_bf16_f32 v76, v94, v95
	v_cvt_pk_bf16_f32 v77, v96, v97
	v_cvt_pk_bf16_f32 v70, v66, v67
	v_cvt_pk_bf16_f32 v71, v68, v69
	v_cvt_pk_bf16_f32 v72, v101, v102
	v_cvt_pk_bf16_f32 v73, v103, v73
	v_cvt_pk_bf16_f32 v66, v104, v105
	v_cvt_pk_bf16_f32 v67, v106, v107
	v_cvt_pk_bf16_f32 v68, v108, v109
	v_cvt_pk_bf16_f32 v69, v110, v99
	s_cbranch_vccz .LBB0_130
	s_and_saveexec_b64 s[10:11], s[4:5]
	ds_write_b32 v232, v98 offset:128
	s_or_b64 exec, exec, s[10:11]
	s_waitcnt lgkmcnt(0)
	v_add_u32_e32 v96, v196, v202
	ds_read_b128 v[84:87], v96 offset:224
	ds_read_b128 v[88:91], v96 offset:192
	ds_read_b128 v[92:95], v96 offset:160
	ds_read_b128 v[100:103], v96 offset:128
	s_waitcnt lgkmcnt(3)
	v_pk_mul_f32 v[14:15], v[14:15], v[84:85]
	s_waitcnt lgkmcnt(2)
	v_pk_mul_f32 v[10:11], v[10:11], v[88:89]
	s_waitcnt lgkmcnt(1)
	v_pk_mul_f32 v[6:7], v[6:7], v[92:93]
	v_pk_mul_f32 v[16:17], v[16:17], v[86:87]
	v_pk_mul_f32 v[12:13], v[12:13], v[90:91]
	v_pk_mul_f32 v[8:9], v[8:9], v[94:95]
	s_waitcnt lgkmcnt(0)
	v_pk_mul_f32 v[4:5], v[4:5], v[102:103]
	v_pk_mul_f32 v[2:3], v[2:3], v[100:101]
	v_pk_mul_f32 v[30:31], v[30:31], v[84:85]
	v_pk_mul_f32 v[26:27], v[26:27], v[88:89]
	v_pk_mul_f32 v[22:23], v[22:23], v[92:93]
	v_pk_mul_f32 v[32:33], v[32:33], v[86:87]
	v_pk_mul_f32 v[28:29], v[28:29], v[90:91]
	v_pk_mul_f32 v[24:25], v[24:25], v[94:95]
	v_pk_mul_f32 v[20:21], v[20:21], v[102:103]
	v_pk_mul_f32 v[18:19], v[18:19], v[100:101]
	v_pk_mul_f32 v[46:47], v[46:47], v[84:85]
	v_pk_mul_f32 v[42:43], v[42:43], v[88:89]
	v_pk_mul_f32 v[38:39], v[38:39], v[92:93]
	v_pk_mul_f32 v[48:49], v[48:49], v[86:87]
	v_pk_mul_f32 v[44:45], v[44:45], v[90:91]
	v_pk_mul_f32 v[40:41], v[40:41], v[94:95]
	v_pk_mul_f32 v[36:37], v[36:37], v[102:103]
	v_pk_mul_f32 v[34:35], v[34:35], v[100:101]
	v_pk_mul_f32 v[62:63], v[62:63], v[84:85]
	v_pk_mul_f32 v[58:59], v[58:59], v[88:89]
	v_pk_mul_f32 v[54:55], v[54:55], v[92:93]
	v_pk_mul_f32 v[64:65], v[64:65], v[86:87]
	v_pk_mul_f32 v[60:61], v[60:61], v[90:91]
	v_pk_mul_f32 v[56:57], v[56:57], v[94:95]
	v_pk_mul_f32 v[52:53], v[52:53], v[102:103]
	v_pk_mul_f32 v[50:51], v[50:51], v[100:101]

.LBB0_169:
	v_add_u32_e32 v6, v136, v130
	ds_read_b128 v[2:5], v6 offset:16384
	ds_read_b128 v[18:21], v6 offset:20480
	v_add_u32_e32 v38, v136, v131
	ds_read_b128 v[34:37], v38 offset:16384
	ds_read_b128 v[38:41], v38 offset:20480
	s_waitcnt lgkmcnt(3)
	v_mfma_f32_32x32x16_bf16 v[2:17], v[2:5], v[82:85], 0
	s_waitcnt lgkmcnt(2)
	v_mfma_f32_32x32x16_bf16 v[18:33], v[18:21], v[82:85], 0
	s_waitcnt lgkmcnt(1)
	v_mfma_f32_32x32x16_bf16 v[2:17], v[34:37], v[86:89], v[2:17]
	s_waitcnt lgkmcnt(0)
	v_mfma_f32_32x32x16_bf16 v[18:33], v[38:41], v[86:89], v[18:33]
	v_add_u32_e32 v38, v136, v132
	ds_read_b128 v[34:37], v38 offset:16384
	ds_read_b128 v[38:41], v38 offset:20480
	s_waitcnt lgkmcnt(1)
	v_mfma_f32_32x32x16_bf16 v[2:17], v[34:37], v[90:93], v[2:17]
	s_waitcnt lgkmcnt(0)
	v_mfma_f32_32x32x16_bf16 v[18:33], v[38:41], v[90:93], v[18:33]
	v_add_u32_e32 v38, v136, v133
	ds_read_b128 v[34:37], v38 offset:16384
	ds_read_b128 v[38:41], v38 offset:20480
	s_waitcnt lgkmcnt(1)
	v_mfma_f32_32x32x16_bf16 v[2:17], v[34:37], v[94:97], v[2:17]
	s_waitcnt lgkmcnt(0)
	v_mfma_f32_32x32x16_bf16 v[18:33], v[38:41], v[94:97], v[18:33]
	s_nop 9
	s_nop 0
	s_nop 0
	v_max_f32_e32 v34, v3, v2
	v_max3_f32 v34, v34, v4, v5
	v_max3_f32 v34, v34, v6, v7
	v_max3_f32 v34, v34, v8, v9
	v_max3_f32 v34, v34, v10, v11
	v_max3_f32 v34, v34, v12, v13
	v_max3_f32 v34, v34, v14, v15
	v_max3_f32 v34, v34, v16, v17
	v_max3_f32 v34, v34, v18, v19
	v_max3_f32 v34, v34, v20, v21
	v_max3_f32 v34, v34, v22, v23
	v_max3_f32 v34, v34, v24, v25
	v_max3_f32 v34, v34, v26, v27
	v_max3_f32 v34, v34, v28, v29
	v_max3_f32 v34, v34, v30, v31
	v_max3_f32 v34, v34, v32, v33
	v_mov_b32_e32 v35, v34
	s_nop 1
	v_permlane32_swap_b32_e32 v34, v35
	s_nop 0
	s_nop 0
	v_max_f32_e32 v35, v35, v34
	v_sub_f32_e32 v2, v2, v35
	v_sub_f32_e32 v3, v3, v35
	v_exp_f32_e32 v2, v2
	v_sub_f32_e32 v4, v4, v35
	v_exp_f32_e32 v3, v3
	v_sub_f32_e32 v5, v5, v35
	v_exp_f32_e32 v4, v4
	v_sub_f32_e32 v18, v18, v35
	v_sub_f32_e32 v6, v6, v35
	v_exp_f32_e32 v5, v5
	v_sub_f32_e32 v7, v7, v35
	v_exp_f32_e32 v6, v6
	v_exp_f32_e32 v37, v18
	v_add_f32_e32 v18, 0, v2
	v_sub_f32_e32 v8, v8, v35
	v_exp_f32_e32 v7, v7
	v_add_f32_e32 v18, v3, v18
	v_sub_f32_e32 v9, v9, v35
	v_exp_f32_e32 v8, v8
	v_add_f32_e32 v18, v4, v18
	v_sub_f32_e32 v10, v10, v35
	v_exp_f32_e32 v9, v9
	v_add_f32_e32 v18, v5, v18
	v_sub_f32_e32 v11, v11, v35
	v_exp_f32_e32 v10, v10
	v_add_f32_e32 v18, v6, v18
	v_sub_f32_e32 v12, v12, v35
	v_exp_f32_e32 v11, v11
	v_add_f32_e32 v18, v7, v18
	v_sub_f32_e32 v13, v13, v35
	v_exp_f32_e32 v12, v12
	v_add_f32_e32 v18, v8, v18
	v_sub_f32_e32 v14, v14, v35
	v_exp_f32_e32 v13, v13
	v_add_f32_e32 v18, v9, v18
	v_sub_f32_e32 v15, v15, v35
	v_exp_f32_e32 v14, v14
	v_add_f32_e32 v18, v10, v18
	v_sub_f32_e32 v16, v16, v35
	v_exp_f32_e32 v15, v15
	v_add_f32_e32 v18, v11, v18
	v_sub_f32_e32 v17, v17, v35
	v_exp_f32_e32 v16, v16
	v_add_f32_e32 v18, v12, v18
	v_exp_f32_e32 v17, v17
	v_add_f32_e32 v18, v13, v18
	v_sub_f32_e32 v19, v19, v35
	v_add_f32_e32 v18, v14, v18
	v_sub_f32_e32 v20, v20, v35
	v_exp_f32_e32 v42, v19
	v_add_f32_e32 v18, v15, v18
	v_sub_f32_e32 v21, v21, v35
	v_exp_f32_e32 v43, v20
	v_add_f32_e32 v18, v16, v18
	v_sub_f32_e32 v22, v22, v35
	v_exp_f32_e32 v44, v21
	v_add_f32_e32 v18, v17, v18
	v_sub_f32_e32 v23, v23, v35
	v_exp_f32_e32 v22, v22
	v_add_f32_e32 v18, v37, v18
	v_sub_f32_e32 v24, v24, v35
	v_exp_f32_e32 v23, v23
	v_add_f32_e32 v18, v42, v18
	v_sub_f32_e32 v25, v25, v35
	v_exp_f32_e32 v24, v24
	v_add_f32_e32 v18, v43, v18
	v_sub_f32_e32 v26, v26, v35
	v_exp_f32_e32 v25, v25
	v_add_f32_e32 v18, v44, v18
	v_sub_f32_e32 v27, v27, v35
	v_exp_f32_e32 v26, v26
	v_add_f32_e32 v18, v22, v18
	v_sub_f32_e32 v28, v28, v35
	v_exp_f32_e32 v27, v27
	v_add_f32_e32 v18, v23, v18
	v_sub_f32_e32 v29, v29, v35
	v_exp_f32_e32 v28, v28
	v_add_f32_e32 v18, v24, v18
	v_sub_f32_e32 v30, v30, v35
	v_exp_f32_e32 v29, v29
	v_add_f32_e32 v18, v25, v18
	v_sub_f32_e32 v31, v31, v35
	v_exp_f32_e32 v30, v30
	v_add_f32_e32 v18, v26, v18
	v_sub_f32_e32 v32, v32, v35
	v_exp_f32_e32 v31, v31
	v_add_f32_e32 v18, v27, v18
	v_sub_f32_e32 v33, v33, v35
	v_exp_f32_e32 v32, v32
	v_add_f32_e32 v18, v28, v18
	v_exp_f32_e32 v33, v33
	v_add_f32_e32 v18, v29, v18
	v_add_f32_e32 v18, v30, v18
	v_add_f32_e32 v18, v31, v18
	v_add_f32_e32 v18, v32, v18
	v_add_f32_e32 v34, v33, v18
	v_mov_b32_e32 v36, v34
	s_nop 1
	v_permlane32_swap_b32_e32 v34, v36
	v_cvt_pk_bf16_f32 v18, v2, v3
	v_cvt_pk_bf16_f32 v19, v4, v5
	v_cvt_pk_bf16_f32 v20, v6, v7
	v_cvt_pk_bf16_f32 v21, v8, v9
	v_cvt_pk_bf16_f32 v38, v10, v11
	v_cvt_pk_bf16_f32 v39, v12, v13
	v_cvt_pk_bf16_f32 v40, v14, v15
	v_cvt_pk_bf16_f32 v41, v16, v17
	v_cvt_pk_bf16_f32 v42, v37, v42
	v_cvt_pk_bf16_f32 v43, v43, v44
	v_cvt_pk_bf16_f32 v44, v22, v23
	v_cvt_pk_bf16_f32 v45, v24, v25
	v_cvt_pk_bf16_f32 v46, v26, v27
	v_cvt_pk_bf16_f32 v47, v28, v29
	v_cvt_pk_bf16_f32 v48, v30, v31
	v_cvt_pk_bf16_f32 v49, v32, v33
	ds_read_b64_tr_b16 v[2:3], v135 offset:0
	ds_read_b64_tr_b16 v[4:5], v135 offset:0x400
	ds_read_b64_tr_b16 v[22:23], v135 offset:0x800
	ds_read_b64_tr_b16 v[24:25], v135 offset:0xc00
	ds_read_b64_tr_b16 v[26:27], v135 offset:0x1000
	ds_read_b64_tr_b16 v[28:29], v135 offset:0x1400
	ds_read_b64_tr_b16 v[30:31], v135 offset:0x1800
	ds_read_b64_tr_b16 v[32:33], v135 offset:0x1c00
	s_waitcnt lgkmcnt(0)
	s_nop 0
	v_mfma_f32_32x32x16_bf16 v[2:17], v[18:21], v[2:5], 0
	v_mfma_f32_32x32x16_bf16 v[2:17], v[38:41], v[22:25], v[2:17]
	ds_read_b64_tr_b16 v[22:23], v135 offset:0x200
	ds_read_b64_tr_b16 v[24:25], v135 offset:0x600
	ds_read_b64_tr_b16 v[50:51], v135 offset:0xa00
	ds_read_b64_tr_b16 v[52:53], v135 offset:0xe00
	ds_read_b64_tr_b16 v[54:55], v135 offset:0x1200
	ds_read_b64_tr_b16 v[56:57], v135 offset:0x1600
	ds_read_b64_tr_b16 v[58:59], v135 offset:0x1a00
	v_mfma_f32_32x32x16_bf16 v[2:17], v[42:45], v[26:29], v[2:17]
	ds_read_b64_tr_b16 v[60:61], v135 offset:0x1e00
	s_waitcnt lgkmcnt(0)
	v_mfma_f32_32x32x16_bf16 v[2:17], v[46:49], v[30:33], v[2:17]
	v_mfma_f32_32x32x16_bf16 v[18:33], v[18:21], v[22:25], 0
	v_cndmask_b32_e64 v37, 0, 1, s[8:9]
	v_cmp_ne_u32_e64 s[74:75], 1, v37
	s_andn2_b64 vcc, exec, s[8:9]
	v_mfma_f32_32x32x16_bf16 v[18:33], v[38:41], v[50:53], v[18:33]
	v_mfma_f32_32x32x16_bf16 v[18:33], v[42:45], v[54:57], v[18:33]
	v_mfma_f32_32x32x16_bf16 v[18:33], v[46:49], v[58:61], v[18:33]
	s_cbranch_vccnz .LBB0_171
	s_waitcnt vmcnt(0)
	ds_write_b128 v113, v[102:105] offset:8192
	ds_write_b128 v117, v[98:101] offset:24576

.LBB0_176:
	s_and_b32 s39, s38, 0x2000
	v_add_u32_e32 v107, s39, v136
	v_add_u32_e32 v54, v107, v130
	ds_read_b128 v[50:53], v54 offset:16384
	ds_read_b128 v[174:177], v54 offset:20480
	v_add_u32_e32 v173, v107, v131
	s_waitcnt lgkmcnt(1)
	v_mfma_f32_32x32x16_bf16 v[66:81], v[50:53], v[82:85], v[34:49]
	v_mov_b64_e32 v[64:65], v[48:49]
	v_mov_b64_e32 v[62:63], v[46:47]
	v_mov_b64_e32 v[60:61], v[44:45]
	v_mov_b64_e32 v[58:59], v[42:43]
	v_mov_b64_e32 v[56:57], v[40:41]
	v_mov_b64_e32 v[54:55], v[38:39]
	v_mov_b64_e32 v[52:53], v[36:37]
	v_mov_b64_e32 v[50:51], v[34:35]
	s_waitcnt lgkmcnt(0)
	s_nop 0
	v_mfma_f32_32x32x16_bf16 v[50:65], v[174:177], v[82:85], v[50:65]
	ds_read_b128 v[174:177], v173 offset:16384
	ds_read_b128 v[180:183], v173 offset:20480
	v_add_u32_e32 v173, v107, v132
	v_add_u32_e32 v107, v107, v133
	s_waitcnt lgkmcnt(1)
	v_mfma_f32_32x32x16_bf16 v[66:81], v[174:177], v[86:89], v[66:81]
	s_waitcnt lgkmcnt(0)
	v_mfma_f32_32x32x16_bf16 v[50:65], v[180:183], v[86:89], v[50:65]
	ds_read_b128 v[174:177], v173 offset:16384
	ds_read_b128 v[180:183], v173 offset:20480
	s_waitcnt lgkmcnt(1)
	v_mfma_f32_32x32x16_bf16 v[66:81], v[174:177], v[90:93], v[66:81]
	s_waitcnt lgkmcnt(0)
	v_mfma_f32_32x32x16_bf16 v[50:65], v[180:183], v[90:93], v[50:65]
	ds_read_b128 v[174:177], v107 offset:16384
	ds_read_b128 v[180:183], v107 offset:20480
	s_waitcnt lgkmcnt(1)
	v_mfma_f32_32x32x16_bf16 v[66:81], v[174:177], v[94:97], v[66:81]
	s_waitcnt lgkmcnt(0)
	v_mfma_f32_32x32x16_bf16 v[50:65], v[180:183], v[94:97], v[50:65]
	s_nop 9
	s_nop 0
	s_nop 0
	v_max_f32_e32 v107, v67, v66
	v_max3_f32 v107, v107, v68, v69
	v_max3_f32 v107, v107, v70, v71
	v_max3_f32 v107, v107, v72, v73
	v_max3_f32 v107, v107, v74, v75
	v_max3_f32 v107, v107, v76, v77
	v_max3_f32 v107, v107, v78, v79
	v_max3_f32 v107, v107, v80, v81
	v_max3_f32 v107, v107, v50, v51
	v_max3_f32 v107, v107, v52, v53
	v_max3_f32 v107, v107, v54, v55
	v_max3_f32 v107, v107, v56, v57
	v_max3_f32 v107, v107, v58, v59
	v_max3_f32 v107, v107, v60, v61
	v_max3_f32 v107, v107, v62, v63
	v_max3_f32 v107, v107, v64, v65
	v_mov_b32_e32 v173, v107
	s_nop 1
	v_permlane32_swap_b32_e32 v107, v173
	s_nop 0
	s_nop 0
	v_max_f32_e32 v173, v173, v107
	v_cmp_ge_f32_e32 vcc, s64, v173
	s_cmp_eq_u64 vcc, exec
	v_mov_b32_e32 v107, 1.0
	s_cbranch_scc0 .LBB0_183

.LBB0_202:
	v_add_u32_e32 v129, v136, v130
	ds_read_b128 v[2:5], v129 offset:16384
	ds_read_b128 v[18:21], v129 offset:20480
	v_add_u32_e32 v173, v136, v131
	ds_read_b128 v[34:37], v173 offset:16384
	ds_read_b128 v[38:41], v173 offset:20480
	v_add_u32_e32 v174, v136, v132
	s_waitcnt lgkmcnt(3)
	v_mfma_f32_32x32x16_bf16 v[2:17], v[2:5], v[84:87], 0
	v_add_u32_e32 v175, v136, v133
	s_waitcnt lgkmcnt(2)
	v_mfma_f32_32x32x16_bf16 v[18:33], v[18:21], v[84:87], 0
	s_waitcnt lgkmcnt(1)
	v_mfma_f32_32x32x16_bf16 v[2:17], v[34:37], v[88:91], v[2:17]
	s_waitcnt lgkmcnt(0)
	v_mfma_f32_32x32x16_bf16 v[18:33], v[38:41], v[88:91], v[18:33]
	ds_read_b128 v[34:37], v174 offset:16384
	ds_read_b128 v[38:41], v174 offset:20480
	s_waitcnt lgkmcnt(1)
	v_mfma_f32_32x32x16_bf16 v[2:17], v[34:37], v[92:95], v[2:17]
	s_waitcnt lgkmcnt(0)
	v_mfma_f32_32x32x16_bf16 v[18:33], v[38:41], v[92:95], v[18:33]
	ds_read_b128 v[34:37], v175 offset:16384
	ds_read_b128 v[38:41], v175 offset:20480
	s_waitcnt lgkmcnt(1)
	v_mfma_f32_32x32x16_bf16 v[2:17], v[34:37], v[96:99], v[2:17]
	s_waitcnt lgkmcnt(0)
	v_mfma_f32_32x32x16_bf16 v[18:33], v[38:41], v[96:99], v[18:33]
	s_nop 9
	s_nop 0
	s_nop 0
	v_max_f32_e32 v0, v3, v2
	v_max3_f32 v0, v0, v4, v5
	v_max3_f32 v0, v0, v6, v7
	v_max3_f32 v0, v0, v8, v9
	v_max3_f32 v0, v0, v10, v11
	v_max3_f32 v0, v0, v12, v13
	v_max3_f32 v0, v0, v14, v15
	v_max3_f32 v0, v0, v16, v17
	v_max3_f32 v0, v0, v18, v19
	v_max3_f32 v0, v0, v20, v21
	v_max3_f32 v0, v0, v22, v23
	v_max3_f32 v0, v0, v24, v25
	v_max3_f32 v0, v0, v26, v27
	v_max3_f32 v0, v0, v28, v29
	v_max3_f32 v0, v0, v30, v31
	v_max3_f32 v0, v0, v32, v33
	v_mov_b32_e32 v34, v0
	s_nop 1
	v_permlane32_swap_b32_e32 v0, v34
	s_nop 0
	s_nop 0
	v_max_f32_e32 v0, v34, v0
	v_sub_f32_e32 v2, v2, v0
	v_sub_f32_e32 v3, v3, v0
	v_exp_f32_e32 v2, v2
	v_sub_f32_e32 v4, v4, v0
	v_exp_f32_e32 v3, v3
	v_sub_f32_e32 v5, v5, v0
	v_exp_f32_e32 v4, v4
	v_sub_f32_e32 v18, v18, v0
	v_sub_f32_e32 v6, v6, v0
	v_exp_f32_e32 v5, v5
	v_sub_f32_e32 v7, v7, v0
	v_exp_f32_e32 v6, v6
	v_exp_f32_e32 v40, v18
	v_add_f32_e32 v18, 0, v2
	v_sub_f32_e32 v8, v8, v0
	v_exp_f32_e32 v7, v7
	v_add_f32_e32 v18, v3, v18
	v_sub_f32_e32 v9, v9, v0
	v_exp_f32_e32 v8, v8
	v_add_f32_e32 v18, v4, v18
	v_sub_f32_e32 v10, v10, v0
	v_exp_f32_e32 v9, v9
	v_add_f32_e32 v18, v5, v18
	v_sub_f32_e32 v11, v11, v0
	v_exp_f32_e32 v10, v10
	v_add_f32_e32 v18, v6, v18
	v_sub_f32_e32 v12, v12, v0
	v_exp_f32_e32 v11, v11
	v_add_f32_e32 v18, v7, v18
	v_sub_f32_e32 v13, v13, v0
	v_exp_f32_e32 v12, v12
	v_add_f32_e32 v18, v8, v18
	v_sub_f32_e32 v14, v14, v0
	v_exp_f32_e32 v13, v13
	v_add_f32_e32 v18, v9, v18
	v_sub_f32_e32 v15, v15, v0
	v_exp_f32_e32 v14, v14
	v_add_f32_e32 v18, v10, v18
	v_sub_f32_e32 v16, v16, v0
	v_exp_f32_e32 v15, v15
	v_add_f32_e32 v18, v11, v18
	v_sub_f32_e32 v17, v17, v0
	v_exp_f32_e32 v16, v16
	v_add_f32_e32 v18, v12, v18
	v_exp_f32_e32 v17, v17
	v_add_f32_e32 v18, v13, v18
	v_sub_f32_e32 v19, v19, v0
	v_add_f32_e32 v18, v14, v18
	v_sub_f32_e32 v20, v20, v0
	v_exp_f32_e32 v41, v19
	v_add_f32_e32 v18, v15, v18
	v_sub_f32_e32 v21, v21, v0
	v_exp_f32_e32 v42, v20
	v_add_f32_e32 v18, v16, v18
	v_sub_f32_e32 v22, v22, v0
	v_exp_f32_e32 v43, v21
	v_add_f32_e32 v18, v17, v18
	v_sub_f32_e32 v23, v23, v0
	v_exp_f32_e32 v22, v22
	v_add_f32_e32 v18, v40, v18
	v_sub_f32_e32 v24, v24, v0
	v_exp_f32_e32 v23, v23
	v_add_f32_e32 v18, v41, v18
	v_sub_f32_e32 v25, v25, v0
	v_exp_f32_e32 v24, v24
	v_add_f32_e32 v18, v42, v18
	v_sub_f32_e32 v26, v26, v0
	v_exp_f32_e32 v25, v25
	v_add_f32_e32 v18, v43, v18
	v_sub_f32_e32 v27, v27, v0
	v_exp_f32_e32 v26, v26
	v_add_f32_e32 v18, v22, v18
	v_sub_f32_e32 v28, v28, v0
	v_exp_f32_e32 v27, v27
	v_add_f32_e32 v18, v23, v18
	v_sub_f32_e32 v29, v29, v0
	v_exp_f32_e32 v28, v28
	v_add_f32_e32 v18, v24, v18
	v_sub_f32_e32 v30, v30, v0
	v_exp_f32_e32 v29, v29
	v_add_f32_e32 v18, v25, v18
	v_sub_f32_e32 v31, v31, v0
	v_exp_f32_e32 v30, v30
	v_add_f32_e32 v18, v26, v18
	v_sub_f32_e32 v32, v32, v0
	v_exp_f32_e32 v31, v31
	v_add_f32_e32 v18, v27, v18
	v_sub_f32_e32 v33, v33, v0
	v_exp_f32_e32 v32, v32
	v_add_f32_e32 v18, v28, v18
	v_exp_f32_e32 v33, v33
	v_add_f32_e32 v18, v29, v18
	v_add_f32_e32 v18, v30, v18
	v_add_f32_e32 v18, v31, v18
	v_add_f32_e32 v18, v32, v18
	v_add_f32_e32 v34, v33, v18
	v_mov_b32_e32 v35, v34
	s_nop 1
	v_permlane32_swap_b32_e32 v34, v35
	v_cvt_pk_bf16_f32 v18, v2, v3
	v_cvt_pk_bf16_f32 v19, v4, v5
	v_cvt_pk_bf16_f32 v20, v6, v7
	v_cvt_pk_bf16_f32 v21, v8, v9
	v_cvt_pk_bf16_f32 v36, v10, v11
	v_cvt_pk_bf16_f32 v37, v12, v13
	v_cvt_pk_bf16_f32 v38, v14, v15
	v_cvt_pk_bf16_f32 v39, v16, v17
	v_cvt_pk_bf16_f32 v40, v40, v41
	v_cvt_pk_bf16_f32 v41, v42, v43
	v_cvt_pk_bf16_f32 v42, v22, v23
	v_cvt_pk_bf16_f32 v43, v24, v25
	v_cvt_pk_bf16_f32 v44, v26, v27
	v_cvt_pk_bf16_f32 v45, v28, v29
	v_cvt_pk_bf16_f32 v46, v30, v31
	v_cvt_pk_bf16_f32 v47, v32, v33
	ds_read_b64_tr_b16 v[2:3], v135 offset:0
	ds_read_b64_tr_b16 v[4:5], v135 offset:0x400
	ds_read_b64_tr_b16 v[22:23], v135 offset:0x800
	ds_read_b64_tr_b16 v[24:25], v135 offset:0xc00
	ds_read_b64_tr_b16 v[26:27], v135 offset:0x1000
	ds_read_b64_tr_b16 v[28:29], v135 offset:0x1400
	ds_read_b64_tr_b16 v[30:31], v135 offset:0x1800
	ds_read_b64_tr_b16 v[32:33], v135 offset:0x1c00
	s_waitcnt lgkmcnt(0)
	s_nop 0
	v_mfma_f32_32x32x16_bf16 v[2:17], v[18:21], v[2:5], 0
	v_mfma_f32_32x32x16_bf16 v[2:17], v[36:39], v[22:25], v[2:17]
	ds_read_b64_tr_b16 v[22:23], v135 offset:0x200
	ds_read_b64_tr_b16 v[24:25], v135 offset:0x600
	ds_read_b64_tr_b16 v[48:49], v135 offset:0xa00
	ds_read_b64_tr_b16 v[50:51], v135 offset:0xe00
	ds_read_b64_tr_b16 v[52:53], v135 offset:0x1200
	ds_read_b64_tr_b16 v[54:55], v135 offset:0x1600
	ds_read_b64_tr_b16 v[56:57], v135 offset:0x1a00
	v_mfma_f32_32x32x16_bf16 v[2:17], v[40:43], v[26:29], v[2:17]
	ds_read_b64_tr_b16 v[58:59], v135 offset:0x1e00
	s_waitcnt lgkmcnt(0)
	v_mfma_f32_32x32x16_bf16 v[2:17], v[44:47], v[30:33], v[2:17]
	v_mfma_f32_32x32x16_bf16 v[18:33], v[18:21], v[22:25], 0
	v_mfma_f32_32x32x16_bf16 v[18:33], v[36:39], v[48:51], v[18:33]
	v_cndmask_b32_e64 v36, 0, 1, vcc
	v_cmp_ne_u32_e64 s[74:75], 1, v36
	s_andn2_b64 vcc, exec, vcc
	v_mfma_f32_32x32x16_bf16 v[18:33], v[40:43], v[52:55], v[18:33]
	v_mfma_f32_32x32x16_bf16 v[18:33], v[44:47], v[56:59], v[18:33]
	s_cbranch_vccnz .LBB0_204
	s_waitcnt vmcnt(0)
	ds_write_b128 v113, v[104:107] offset:8192
	ds_write_b128 v117, v[100:103] offset:24576

.LBB0_207:
	v_add_f32_e32 v0, 0, v0
	v_xor_b32_e32 v34, 0x80000000, v0
	v_mov_b32_e32 v35, v34
	v_mov_b32_e32 v36, v34
	v_mov_b32_e32 v37, v34
	v_mov_b32_e32 v38, v34
	v_mov_b32_e32 v39, v34
	v_mov_b32_e32 v40, v34
	v_mov_b32_e32 v41, v34
	v_mov_b32_e32 v42, v34
	v_mov_b32_e32 v43, v34
	v_mov_b32_e32 v44, v34
	v_mov_b32_e32 v45, v34
	v_mov_b32_e32 v46, v34
	v_mov_b32_e32 v47, v34
	v_mov_b32_e32 v48, v34
	v_mov_b32_e32 v49, v34
	ds_read_b128 v[50:53], v129 offset:24576
	ds_read_b128 v[180:183], v129 offset:28672
	s_waitcnt lgkmcnt(1)
	v_mfma_f32_32x32x16_bf16 v[68:83], v[50:53], v[84:87], v[34:49]
	v_mov_b64_e32 v[66:67], v[48:49]
	v_mov_b64_e32 v[64:65], v[46:47]
	v_mov_b64_e32 v[62:63], v[44:45]
	v_mov_b64_e32 v[60:61], v[42:43]
	v_mov_b64_e32 v[58:59], v[40:41]
	v_mov_b64_e32 v[56:57], v[38:39]
	v_mov_b64_e32 v[54:55], v[36:37]
	v_mov_b64_e32 v[52:53], v[34:35]
	ds_read_b128 v[36:39], v173 offset:24576
	ds_read_b128 v[40:43], v173 offset:28672
	s_waitcnt lgkmcnt(2)
	v_mfma_f32_32x32x16_bf16 v[52:67], v[180:183], v[84:87], v[52:67]
	s_waitcnt lgkmcnt(1)
	v_mfma_f32_32x32x16_bf16 v[68:83], v[36:39], v[88:91], v[68:83]
	s_waitcnt lgkmcnt(0)
	v_mfma_f32_32x32x16_bf16 v[52:67], v[40:43], v[88:91], v[52:67]
	ds_read_b128 v[36:39], v174 offset:24576
	ds_read_b128 v[40:43], v174 offset:28672
	s_waitcnt lgkmcnt(1)
	v_mfma_f32_32x32x16_bf16 v[68:83], v[36:39], v[92:95], v[68:83]
	s_waitcnt lgkmcnt(0)
	v_mfma_f32_32x32x16_bf16 v[52:67], v[40:43], v[92:95], v[52:67]
	ds_read_b128 v[36:39], v175 offset:24576
	ds_read_b128 v[40:43], v175 offset:28672
	s_waitcnt lgkmcnt(1)
	v_mfma_f32_32x32x16_bf16 v[68:83], v[36:39], v[96:99], v[68:83]
	s_waitcnt lgkmcnt(0)
	v_mfma_f32_32x32x16_bf16 v[52:67], v[40:43], v[96:99], v[52:67]
	s_nop 9
	s_nop 0
	s_nop 0
	v_max_f32_e32 v35, v69, v68
	v_max3_f32 v35, v35, v70, v71
	v_max3_f32 v35, v35, v72, v73
	v_max3_f32 v35, v35, v74, v75
	v_max3_f32 v35, v35, v76, v77
	v_max3_f32 v35, v35, v78, v79
	v_max3_f32 v35, v35, v80, v81
	v_max3_f32 v35, v35, v82, v83
	v_max3_f32 v35, v35, v52, v53
	v_max3_f32 v35, v35, v54, v55
	v_max3_f32 v35, v35, v56, v57
	v_max3_f32 v35, v35, v58, v59
	v_max3_f32 v35, v35, v60, v61
	v_max3_f32 v35, v35, v62, v63
	v_max3_f32 v35, v35, v64, v65
	v_max3_f32 v35, v35, v66, v67
	v_mov_b32_e32 v36, v35
	s_nop 1
	v_permlane32_swap_b32_e32 v35, v36
	s_nop 0
	s_nop 0
	v_max_f32_e32 v35, v36, v35
	v_cmp_ge_f32_e32 vcc, s64, v35
	s_cmp_eq_u64 vcc, exec
	s_cbranch_scc0 .LBB0_263
	v_mov_b64_e32 v[50:51], v[48:49]
	v_mov_b32_e32 v176, 1.0
	v_mov_b64_e32 v[48:49], v[46:47]
	v_mov_b64_e32 v[46:47], v[44:45]
	v_mov_b64_e32 v[44:45], v[42:43]
	v_mov_b64_e32 v[42:43], v[40:41]
	v_mov_b64_e32 v[40:41], v[38:39]
	v_mov_b64_e32 v[38:39], v[36:37]
	v_mov_b64_e32 v[36:37], v[34:35]

.LBB0_218:
	v_mov_b32_e32 v37, v34
	v_mov_b32_e32 v38, v34
	v_mov_b32_e32 v39, v34
	v_mov_b32_e32 v40, v34
	v_mov_b32_e32 v41, v34
	v_mov_b32_e32 v42, v34
	v_mov_b32_e32 v43, v34
	v_mov_b32_e32 v44, v34
	v_mov_b32_e32 v45, v34
	v_mov_b32_e32 v46, v34
	v_mov_b32_e32 v47, v34
	v_mov_b32_e32 v48, v34
	v_mov_b32_e32 v49, v34
	v_mov_b32_e32 v50, v34
	v_mov_b32_e32 v51, v34
	ds_read_b128 v[52:55], v129 offset:16384
	ds_read_b128 v[180:183], v129 offset:20480
	s_waitcnt lgkmcnt(1)
	v_mfma_f32_32x32x16_bf16 v[68:83], v[52:55], v[84:87], v[36:51]
	s_waitcnt lgkmcnt(0)
	v_mfma_f32_32x32x16_bf16 v[52:67], v[180:183], v[84:87], v[36:51]
	ds_read_b128 v[180:183], v173 offset:16384
	ds_read_b128 v[184:187], v173 offset:20480
	s_waitcnt lgkmcnt(1)
	v_mfma_f32_32x32x16_bf16 v[68:83], v[180:183], v[88:91], v[68:83]
	s_waitcnt lgkmcnt(0)
	v_mfma_f32_32x32x16_bf16 v[52:67], v[184:187], v[88:91], v[52:67]
	ds_read_b128 v[180:183], v174 offset:16384
	ds_read_b128 v[184:187], v174 offset:20480
	s_waitcnt lgkmcnt(1)
	v_mfma_f32_32x32x16_bf16 v[68:83], v[180:183], v[92:95], v[68:83]
	s_waitcnt lgkmcnt(0)
	v_mfma_f32_32x32x16_bf16 v[52:67], v[184:187], v[92:95], v[52:67]
	ds_read_b128 v[180:183], v175 offset:16384
	ds_read_b128 v[184:187], v175 offset:20480
	s_waitcnt lgkmcnt(1)
	v_mfma_f32_32x32x16_bf16 v[68:83], v[180:183], v[96:99], v[68:83]
	s_waitcnt lgkmcnt(0)
	v_mfma_f32_32x32x16_bf16 v[52:67], v[184:187], v[96:99], v[52:67]
	s_nop 9
	s_nop 0
	s_nop 0
	v_max_f32_e32 v128, v69, v68
	v_max3_f32 v128, v128, v70, v71
	v_max3_f32 v128, v128, v72, v73
	v_max3_f32 v128, v128, v74, v75
	v_max3_f32 v128, v128, v76, v77
	v_max3_f32 v128, v128, v78, v79
	v_max3_f32 v128, v128, v80, v81
	v_max3_f32 v128, v128, v82, v83
	v_max3_f32 v128, v128, v52, v53
	v_max3_f32 v128, v128, v54, v55
	v_max3_f32 v128, v128, v56, v57
	v_max3_f32 v128, v128, v58, v59
	v_max3_f32 v128, v128, v60, v61
	v_max3_f32 v128, v128, v62, v63
	v_max3_f32 v128, v128, v64, v65
	v_max3_f32 v128, v128, v66, v67
	v_mov_b32_e32 v176, v128
	s_nop 1
	v_permlane32_swap_b32_e32 v128, v176
	s_nop 0
	s_nop 0
	v_max_f32_e32 v176, v176, v128
	v_cmp_ge_f32_e32 vcc, s64, v176
	s_cmp_eq_u64 vcc, exec
	v_mov_b32_e32 v128, 1.0
	s_cbranch_scc0 .LBB0_264

.LBB0_228:
	ds_read_b128 v[70:73], v129 offset:24576
	ds_read_b128 v[74:77], v129 offset:28672
	s_waitcnt lgkmcnt(1)
	v_mfma_f32_32x32x16_bf16 v[52:67], v[70:73], v[84:87], v[36:51]
	s_waitcnt lgkmcnt(0)
	v_mfma_f32_32x32x16_bf16 v[36:51], v[74:77], v[84:87], v[36:51]
	ds_read_b128 v[70:73], v173 offset:24576
	ds_read_b128 v[74:77], v173 offset:28672
	s_waitcnt lgkmcnt(1)
	v_mfma_f32_32x32x16_bf16 v[52:67], v[70:73], v[88:91], v[52:67]
	s_waitcnt lgkmcnt(0)
	v_mfma_f32_32x32x16_bf16 v[36:51], v[74:77], v[88:91], v[36:51]
	ds_read_b128 v[70:73], v174 offset:24576
	ds_read_b128 v[74:77], v174 offset:28672
	s_waitcnt lgkmcnt(1)
	v_mfma_f32_32x32x16_bf16 v[52:67], v[70:73], v[92:95], v[52:67]
	s_waitcnt lgkmcnt(0)
	v_mfma_f32_32x32x16_bf16 v[36:51], v[74:77], v[92:95], v[36:51]
	ds_read_b128 v[70:73], v175 offset:24576
	ds_read_b128 v[74:77], v175 offset:28672
	s_waitcnt lgkmcnt(1)
	v_mfma_f32_32x32x16_bf16 v[52:67], v[70:73], v[96:99], v[52:67]
	s_waitcnt lgkmcnt(0)
	v_mfma_f32_32x32x16_bf16 v[36:51], v[74:77], v[96:99], v[36:51]
	s_nop 9
	s_nop 0
	s_nop 0
	v_max_f32_e32 v35, v53, v52
	v_max3_f32 v35, v35, v54, v55
	v_max3_f32 v35, v35, v56, v57
	v_max3_f32 v35, v35, v58, v59
	v_max3_f32 v35, v35, v60, v61
	v_max3_f32 v35, v35, v62, v63
	v_max3_f32 v35, v35, v64, v65
	v_max3_f32 v35, v35, v66, v67
	v_max3_f32 v35, v35, v36, v37
	v_max3_f32 v35, v35, v38, v39
	v_max3_f32 v35, v35, v40, v41
	v_max3_f32 v35, v35, v42, v43
	v_max3_f32 v35, v35, v44, v45
	v_max3_f32 v35, v35, v46, v47
	v_max3_f32 v35, v35, v48, v49
	v_max3_f32 v35, v35, v50, v51
	v_mov_b32_e32 v69, v35
	s_nop 1
	v_permlane32_swap_b32_e32 v35, v69
	s_nop 0
	s_nop 0
	v_max_f32_e32 v69, v69, v35
	v_cmp_ge_f32_e32 vcc, s64, v69
	s_cmp_eq_u64 vcc, exec
	v_mov_b32_e32 v35, 1.0
	s_cbranch_scc0 .LBB0_265

.LBB0_242:
	s_add_i32 s40, s39, 4
	s_and_b32 s40, s40, 1
	s_add_i32 s41, s41, -4
	v_cmp_ge_i32_e32 vcc, s41, v173
	v_cmp_lt_i32_e64 s[74:75], s41, v174
	s_and_b64 vcc, vcc, s[74:75]
	s_and_saveexec_b64 s[74:75], vcc
	s_cbranch_execz .LBB0_249
	s_and_b32 s41, s39, 3
	s_lshl_b32 s41, s41, 2
	s_lshr_b32 s41, 0x1650, s41
	s_and_b32 s41, s41, 15
	s_lshl_b32 s41, s41, 13
	v_add_u32_e32 v82, s41, v136
	v_add_u32_e32 v50, v82, v130
	ds_read_b128 v[66:69], v50 offset:16384
	ds_read_b128 v[180:183], v50 offset:20480
	v_add_u32_e32 v83, v82, v131
	v_add_u32_e32 v128, v175, v169
	v_readlane_b32 vcc_lo, v254, 22
	s_waitcnt lgkmcnt(1)
	v_mfma_f32_32x32x16_bf16 v[50:65], v[66:69], v[84:87], v[34:49]
	v_readlane_b32 vcc_hi, v254, 23
	s_waitcnt lgkmcnt(0)
	v_mfma_f32_32x32x16_bf16 v[66:81], v[180:183], v[84:87], v[34:49]
	ds_read_b128 v[180:183], v83 offset:16384
	ds_read_b128 v[184:187], v83 offset:20480
	v_add_u32_e32 v83, v82, v132
	v_add_u32_e32 v82, v82, v133
	s_waitcnt lgkmcnt(0)
	v_mfma_f32_32x32x16_bf16 v[66:81], v[184:187], v[88:91], v[66:81]
	v_mfma_f32_32x32x16_bf16 v[50:65], v[180:183], v[88:91], v[50:65]
	ds_read_b128 v[180:183], v83 offset:16384
	ds_read_b128 v[184:187], v83 offset:20480
	v_add_u32_e32 v83, v175, v171
	s_waitcnt lgkmcnt(0)
	v_mfma_f32_32x32x16_bf16 v[66:81], v[184:187], v[92:95], v[66:81]
	v_mfma_f32_32x32x16_bf16 v[50:65], v[180:183], v[92:95], v[50:65]
	ds_read_b128 v[180:183], v82 offset:16384
	ds_read_b128 v[184:187], v82 offset:20480
	v_add_u32_e32 v82, v175, v172
	ds_read_b32 v82, v82 offset:35260
	ds_read_b32 v83, v83 offset:35260
	ds_read_b32 v128, v128 offset:35260
	s_waitcnt lgkmcnt(3)
	v_mfma_f32_32x32x16_bf16 v[66:81], v[184:187], v[96:99], v[66:81]
	v_mfma_f32_32x32x16_bf16 v[50:65], v[180:183], v[96:99], v[50:65]
	s_waitcnt lgkmcnt(1)
	s_nop 9
	v_add_f32_e32 v66, v66, v83
	v_add_u32_e32 v83, v175, v170
	ds_read_b32 v83, v83 offset:35260
	v_cndmask_b32_e32 v66, v218, v66, vcc
	v_readlane_b32 vcc_lo, v254, 26
	v_readlane_b32 vcc_hi, v254, 27
	s_waitcnt lgkmcnt(0)
	v_pk_add_f32 v[82:83], v[50:51], v[82:83]
	s_nop 0
	v_cndmask_b32_e32 v51, v82, v218, vcc
	v_readlane_b32 vcc_lo, v254, 24
	v_readlane_b32 vcc_hi, v254, 25
	v_add_f32_e32 v50, v67, v128
	s_nop 0
	v_cndmask_b32_e32 v82, v83, v218, vcc
	v_readlane_b32 vcc_lo, v254, 28
	v_readlane_b32 vcc_hi, v254, 29
	s_nop 1
	v_cndmask_b32_e32 v67, v218, v50, vcc
	v_add_u32_e32 v50, v175, v168
	ds_read_b32 v128, v50 offset:35260
	v_add_u32_e32 v50, v175, v167
	ds_read_b32 v50, v50 offset:35260
	v_readlane_b32 vcc_lo, v254, 30
	v_readlane_b32 vcc_hi, v254, 31
	s_waitcnt lgkmcnt(0)
	v_add_f32_e32 v50, v68, v50
	v_cndmask_b32_e32 v68, v218, v50, vcc
	v_add_u32_e32 v50, v175, v166
	ds_read_b32 v129, v50 offset:35260
	v_add_u32_e32 v50, v175, v165
	ds_read_b32 v50, v50 offset:35260
	v_readlane_b32 vcc_lo, v254, 34
	v_readlane_b32 vcc_hi, v254, 35
	s_waitcnt lgkmcnt(1)
	v_pk_add_f32 v[52:53], v[52:53], v[128:129]
	s_waitcnt lgkmcnt(0)
	v_add_f32_e32 v50, v69, v50
	v_cndmask_b32_e32 v83, v52, v218, vcc
	v_readlane_b32 vcc_lo, v254, 32
	v_readlane_b32 vcc_hi, v254, 33
	s_nop 1
	v_cndmask_b32_e32 v128, v53, v218, vcc
	v_readlane_b32 vcc_lo, v254, 36
	v_readlane_b32 vcc_hi, v254, 37
	s_nop 1
	v_cndmask_b32_e32 v69, v218, v50, vcc
	v_add_u32_e32 v50, v175, v164
	ds_read_b32 v180, v50 offset:35260
	v_add_u32_e32 v50, v175, v163
	ds_read_b32 v50, v50 offset:35260
	v_readlane_b32 vcc_lo, v254, 38
	v_readlane_b32 vcc_hi, v254, 39
	s_waitcnt lgkmcnt(0)
	v_add_f32_e32 v50, v70, v50
	v_cndmask_b32_e32 v52, v218, v50, vcc
	v_add_u32_e32 v50, v175, v162
	ds_read_b32 v181, v50 offset:35260
	v_add_u32_e32 v50, v175, v161
	ds_read_b32 v50, v50 offset:35260
	v_readlane_b32 vcc_lo, v254, 42
	v_readlane_b32 vcc_hi, v254, 43
	s_waitcnt lgkmcnt(1)
	v_pk_add_f32 v[54:55], v[54:55], v[180:181]
	s_waitcnt lgkmcnt(0)
	v_add_f32_e32 v50, v71, v50
	v_cndmask_b32_e32 v129, v54, v218, vcc
	v_readlane_b32 vcc_lo, v254, 40
	v_readlane_b32 vcc_hi, v254, 41
	s_nop 1
	v_cndmask_b32_e32 v54, v55, v218, vcc
	v_readlane_b32 vcc_lo, v254, 44
	v_readlane_b32 vcc_hi, v254, 45
	s_nop 1
	v_cndmask_b32_e32 v53, v218, v50, vcc
	v_add_u32_e32 v50, v175, v160
	ds_read_b32 v180, v50 offset:35260
	v_add_u32_e32 v50, v175, v159
	ds_read_b32 v50, v50 offset:35260
	v_readlane_b32 vcc_lo, v254, 46
	v_readlane_b32 vcc_hi, v254, 47
	s_waitcnt lgkmcnt(0)
	v_add_f32_e32 v50, v72, v50
	v_cndmask_b32_e32 v70, v218, v50, vcc
	v_add_u32_e32 v50, v175, v158
	ds_read_b32 v181, v50 offset:35260
	v_add_u32_e32 v50, v175, v157
	ds_read_b32 v50, v50 offset:35260
	v_readlane_b32 vcc_lo, v254, 50
	v_readlane_b32 vcc_hi, v254, 51
	s_waitcnt lgkmcnt(1)
	v_pk_add_f32 v[56:57], v[56:57], v[180:181]
	s_nop 0
	v_cndmask_b32_e32 v55, v56, v218, vcc
	v_readlane_b32 vcc_lo, v254, 48
	v_readlane_b32 vcc_hi, v254, 49
	s_nop 1
	v_cndmask_b32_e32 v56, v57, v218, vcc
	v_readlane_b32 vcc_lo, v254, 52
	v_add_u32_e32 v57, v175, v155
	v_readlane_b32 vcc_hi, v254, 53
	ds_read_b32 v180, v57 offset:35260
	s_waitcnt lgkmcnt(1)
	v_add_f32_e32 v50, v73, v50
	v_cndmask_b32_e32 v71, v218, v50, vcc
	v_add_u32_e32 v50, v175, v156
	ds_read_b32 v50, v50 offset:35260
	v_readlane_b32 vcc_lo, v254, 54
	v_readlane_b32 vcc_hi, v254, 55
	v_add_u32_e32 v73, v175, v151
	s_waitcnt lgkmcnt(0)
	v_add_f32_e32 v50, v58, v50
	v_cndmask_b32_e32 v57, v218, v50, vcc
	v_add_u32_e32 v50, v175, v154
	ds_read_b32 v50, v50 offset:35260
	v_add_u32_e32 v58, v175, v153
	ds_read_b32 v181, v58 offset:35260
	s_waitcnt lgkmcnt(1)
	v_add_f32_e32 v50, v59, v50
	v_cndmask_b32_e64 v72, v218, v50, s[44:45]
	v_add_u32_e32 v50, v175, v152
	ds_read_b32 v50, v50 offset:35260
	s_waitcnt lgkmcnt(1)
	v_pk_add_f32 v[58:59], v[74:75], v[180:181]
	ds_read_b32 v180, v73 offset:35260
	v_add_u32_e32 v75, v175, v147
	v_cndmask_b32_e64 v59, v218, v59, s[10:11]
	s_waitcnt lgkmcnt(1)
	v_add_f32_e32 v50, v60, v50
	v_cndmask_b32_e64 v73, v218, v50, s[50:51]
	v_add_u32_e32 v50, v175, v150
	ds_read_b32 v50, v50 offset:35260
	v_add_u32_e32 v60, v175, v149
	ds_read_b32 v181, v60 offset:35260
	v_cndmask_b32_e64 v58, v218, v58, s[12:13]
	s_waitcnt lgkmcnt(1)
	v_add_f32_e32 v50, v61, v50
	v_cndmask_b32_e64 v74, v218, v50, s[52:53]
	v_add_u32_e32 v50, v175, v148
	ds_read_b32 v50, v50 offset:35260
	s_waitcnt lgkmcnt(1)
	v_pk_add_f32 v[60:61], v[76:77], v[180:181]
	ds_read_b32 v180, v75 offset:35260
	v_add_u32_e32 v77, v175, v143
	v_cndmask_b32_e64 v61, v218, v61, s[14:15]
	s_waitcnt lgkmcnt(1)
	v_add_f32_e32 v50, v62, v50
	v_cndmask_b32_e64 v75, v218, v50, s[58:59]
	v_add_u32_e32 v50, v175, v146
	ds_read_b32 v50, v50 offset:35260
	v_add_u32_e32 v62, v175, v145
	ds_read_b32 v181, v62 offset:35260
	v_cndmask_b32_e64 v60, v218, v60, s[16:17]
	s_waitcnt lgkmcnt(1)
	v_add_f32_e32 v50, v63, v50
	v_cndmask_b32_e64 v76, v218, v50, s[60:61]
	v_add_u32_e32 v50, v175, v144
	ds_read_b32 v50, v50 offset:35260
	s_waitcnt lgkmcnt(1)
	v_pk_add_f32 v[62:63], v[78:79], v[180:181]
	ds_read_b32 v78, v77 offset:35260
	v_cndmask_b32_e64 v63, v218, v63, s[18:19]
	v_cndmask_b32_e64 v62, v218, v62, s[20:21]
	s_waitcnt lgkmcnt(1)
	v_add_f32_e32 v50, v64, v50
	v_add_u32_e32 v64, v175, v142
	v_cndmask_b32_e64 v77, v218, v50, s[66:67]
	s_waitcnt lgkmcnt(0)
	v_add_f32_e32 v50, v80, v78
	ds_read_b32 v64, v64 offset:35260
	v_add_u32_e32 v78, v175, v140
	ds_read_b32 v78, v78 offset:35260
	v_cndmask_b32_e64 v50, v218, v50, s[22:23]
	s_waitcnt lgkmcnt(1)
	v_add_f32_e32 v64, v65, v64
	v_cndmask_b32_e64 v65, v218, v64, s[70:71]
	s_waitcnt lgkmcnt(0)
	v_add_f32_e32 v64, v81, v78
	v_max_f32_e32 v78, v51, v82
	v_max3_f32 v78, v78, v83, v128
	v_max3_f32 v78, v78, v129, v54
	v_max3_f32 v78, v78, v55, v56
	v_max3_f32 v78, v78, v57, v72
	v_max3_f32 v78, v78, v73, v74
	v_max3_f32 v78, v78, v75, v76
	v_max3_f32 v78, v78, v77, v65
	v_max3_f32 v78, v78, v66, v67
	v_max3_f32 v78, v78, v68, v69
	v_max3_f32 v78, v78, v52, v53
	v_max3_f32 v78, v78, v70, v71
	v_max3_f32 v78, v78, v58, v59
	v_max3_f32 v78, v78, v60, v61
	v_cndmask_b32_e64 v64, v218, v64, s[30:31]
	v_max3_f32 v78, v78, v62, v63
	v_max3_f32 v78, v78, v50, v64
	v_mov_b32_e32 v79, v78
	s_nop 1
	v_permlane32_swap_b32_e32 v78, v79
	s_nop 0
	s_nop 0
	v_max_f32_e32 v79, v79, v78
	v_cmp_ge_f32_e32 vcc, s64, v79
	v_mov_b32_e32 v78, 1.0
	s_cmp_eq_u64 vcc, exec
	s_cbranch_scc0 .LBB0_251

.LBB0_285:
	s_lshl_b32 s11, s11, 6
	s_and_b32 s11, s11, 0x100
	s_add_u32 s12, s18, s11
	s_addc_u32 s13, s19, 0
	s_add_u32 s14, s20, s11
	s_addc_u32 s15, s21, 0
	s_ashr_i32 s11, s10, 31
	v_cvt_pk_bf16_f32 v134, v70, v71
	v_cvt_pk_bf16_f32 v135, v72, v73
	v_cvt_pk_bf16_f32 v136, v66, v67
	v_cvt_pk_bf16_f32 v137, v68, v69
	v_cvt_pk_bf16_f32 v142, v62, v63
	v_cvt_pk_bf16_f32 v143, v64, v65
	v_cvt_pk_bf16_f32 v144, v58, v59
	v_cvt_pk_bf16_f32 v145, v60, v61
	v_cvt_pk_bf16_f32 v146, v54, v55
	v_cvt_pk_bf16_f32 v147, v56, v57
	v_cvt_pk_bf16_f32 v148, v50, v51
	v_cvt_pk_bf16_f32 v149, v52, v53
	v_cvt_pk_bf16_f32 v150, v46, v47
	v_cvt_pk_bf16_f32 v151, v48, v49
	v_cvt_pk_bf16_f32 v152, v42, v43
	v_cvt_pk_bf16_f32 v153, v44, v45
	v_cvt_pk_bf16_f32 v154, v38, v39
	v_cvt_pk_bf16_f32 v155, v40, v41
	v_cvt_pk_bf16_f32 v156, v34, v35
	v_cvt_pk_bf16_f32 v157, v32, v33
	v_cvt_pk_bf16_f32 v158, v30, v31
	v_cvt_pk_bf16_f32 v159, v36, v37
	v_cvt_pk_bf16_f32 v160, v78, v81
	v_cvt_pk_bf16_f32 v161, v74, v77
	v_cvt_pk_bf16_f32 v138, v26, v27
	v_cvt_pk_bf16_f32 v139, v28, v29
	v_cvt_pk_bf16_f32 v140, v22, v23
	v_cvt_pk_bf16_f32 v141, v24, v25
	v_cvt_pk_bf16_f32 v130, v18, v19
	v_cvt_pk_bf16_f32 v131, v20, v21
	v_cvt_pk_bf16_f32 v132, v6, v7
	v_cvt_pk_bf16_f32 v133, v2, v3
	v_lshl_add_u64 v[2:3], s[10:11], 0, v[184:185]
	v_mov_b64_e32 v[4:5], s[12:13]
	v_mad_u64_u32 v[6:7], s[24:25], v2, s65, v[4:5]
	v_mad_i32_i24 v7, v3, s65, v7
	v_mov_b32_e32 v195, v1
	v_lshl_add_u64 v[10:11], v[6:7], 0, v[194:195]
	v_lshl_add_u64 v[6:7], v[186:187], 0, s[10:11]
	v_mad_u64_u32 v[4:5], s[24:25], v6, s65, v[4:5]
	v_mad_i32_i24 v5, v7, s65, v5
	v_lshl_add_u64 v[14:15], v[4:5], 0, v[194:195]
	v_mov_b64_e32 v[4:5], s[14:15]
	v_mad_u64_u32 v[8:9], s[24:25], v2, s65, v[4:5]
	v_mad_u64_u32 v[4:5], s[24:25], v6, s65, v[4:5]
	v_mad_i32_i24 v9, v3, s65, v9
	v_mad_i32_i24 v5, v7, s65, v5
	v_lshl_add_u64 v[2:3], v[8:9], 0, v[194:195]
	v_lshl_add_u64 v[6:7], v[4:5], 0, v[194:195]
	global_load_dwordx4 v[2:5], v[2:3], off
	s_nop 0
	global_load_dwordx4 v[6:9], v[6:7], off
	s_nop 0
	global_load_dwordx4 v[10:13], v[10:11], off
	s_nop 0
	global_load_dwordx4 v[14:17], v[14:15], off
	v_lshl_add_u64 v[198:199], s[12:13], 0, v[194:195]
	s_or_b32 s12, s10, 64
	s_ashr_i32 s13, s12, 31
	v_add_u32_e32 v62, 16, v222
	v_lshl_add_u64 v[200:201], s[14:15], 0, v[194:195]
	v_lshl_add_u64 v[18:19], s[12:13], 0, v[184:185]
	v_add_u32_e32 v63, 16, v223
	v_add_u32_e32 v64, 16, v224
	v_add_u32_e32 v67, 16, v225
	v_lshl_add_u64 v[20:21], v[186:187], 0, s[12:13]
	v_mad_u64_u32 v[22:23], s[12:13], v18, s65, v[198:199]
	s_waitcnt vmcnt(0)
	v_mad_u64_u32 v[24:25], s[12:13], v20, s65, v[198:199]
	v_mad_i32_i24 v23, v19, s65, v23
	v_mad_i32_i24 v25, v21, s65, v25
	s_waitcnt vmcnt(3)
	ds_write_b128 v62, v[2:5]
	s_waitcnt vmcnt(2)
	ds_write_b128 v63, v[6:9]
	s_waitcnt vmcnt(1)
	ds_write_b128 v64, v[10:13] offset:32768
	s_waitcnt vmcnt(0)
	ds_write_b128 v67, v[14:17] offset:32768
	v_mad_u64_u32 v[2:3], s[12:13], v18, s65, v[200:201]
	v_mad_i32_i24 v3, v19, s65, v3
	v_mad_u64_u32 v[4:5], s[12:13], v20, s65, v[200:201]
	s_waitcnt lgkmcnt(0)
	s_barrier
	global_load_dwordx4 v[50:53], v[22:23], off
	global_load_dwordx4 v[68:71], v[24:25], off
	v_mad_i32_i24 v5, v21, s65, v5
	global_load_dwordx4 v[54:57], v[2:3], off
	global_load_dwordx4 v[58:61], v[4:5], off
	v_add_u32_e32 v6, v227, v228
	ds_read_b128 v[2:5], v6 offset:32768
	ds_read_b128 v[18:21], v6 offset:40960
	v_add_u32_e32 v38, v227, v229
	ds_read_b128 v[34:37], v38 offset:32768
	ds_read_b128 v[38:41], v38 offset:40960
	s_waitcnt lgkmcnt(3)
	v_mfma_f32_32x32x16_bf16 v[2:17], v[2:5], v[134:137], 0
	s_waitcnt lgkmcnt(2)
	v_mfma_f32_32x32x16_bf16 v[18:33], v[18:21], v[134:137], 0
	s_waitcnt lgkmcnt(1)
	v_mfma_f32_32x32x16_bf16 v[2:17], v[34:37], v[142:145], v[2:17]
	s_waitcnt lgkmcnt(0)
	v_mfma_f32_32x32x16_bf16 v[18:33], v[38:41], v[142:145], v[18:33]
	v_add_u32_e32 v38, v227, v230
	ds_read_b128 v[34:37], v38 offset:32768
	ds_read_b128 v[38:41], v38 offset:40960
	s_waitcnt lgkmcnt(1)
	v_mfma_f32_32x32x16_bf16 v[2:17], v[34:37], v[146:149], v[2:17]
	s_waitcnt lgkmcnt(0)
	v_mfma_f32_32x32x16_bf16 v[18:33], v[38:41], v[146:149], v[18:33]
	v_add_u32_e32 v38, v227, v231
	ds_read_b128 v[34:37], v38 offset:32768
	ds_read_b128 v[38:41], v38 offset:40960
	s_waitcnt lgkmcnt(1)
	v_mfma_f32_32x32x16_bf16 v[2:17], v[34:37], v[150:153], v[2:17]
	s_waitcnt lgkmcnt(0)
	v_mfma_f32_32x32x16_bf16 v[18:33], v[38:41], v[150:153], v[18:33]
	v_add_u32_e32 v38, v227, v232
	ds_read_b128 v[34:37], v38 offset:32768
	ds_read_b128 v[38:41], v38 offset:40960
	s_waitcnt lgkmcnt(1)
	v_mfma_f32_32x32x16_bf16 v[2:17], v[34:37], v[154:157], v[2:17]
	s_waitcnt lgkmcnt(0)
	v_mfma_f32_32x32x16_bf16 v[18:33], v[38:41], v[154:157], v[18:33]
	v_add_u32_e32 v38, v227, v233
	ds_read_b128 v[34:37], v38 offset:32768
	ds_read_b128 v[38:41], v38 offset:40960
	s_waitcnt lgkmcnt(1)
	v_mfma_f32_32x32x16_bf16 v[2:17], v[34:37], v[158:161], v[2:17]
	s_waitcnt lgkmcnt(0)
	v_mfma_f32_32x32x16_bf16 v[18:33], v[38:41], v[158:161], v[18:33]
	v_add_u32_e32 v38, v227, v234
	ds_read_b128 v[34:37], v38 offset:32768
	ds_read_b128 v[38:41], v38 offset:40960
	s_waitcnt lgkmcnt(1)
	v_mfma_f32_32x32x16_bf16 v[2:17], v[34:37], v[138:141], v[2:17]
	s_waitcnt lgkmcnt(0)
	v_mfma_f32_32x32x16_bf16 v[18:33], v[38:41], v[138:141], v[18:33]
	v_add_u32_e32 v38, v227, v235
	ds_read_b128 v[34:37], v38 offset:32768
	ds_read_b128 v[38:41], v38 offset:40960
	s_waitcnt lgkmcnt(1)
	v_mfma_f32_32x32x16_bf16 v[2:17], v[34:37], v[130:133], v[2:17]
	s_waitcnt lgkmcnt(0)
	v_mfma_f32_32x32x16_bf16 v[18:33], v[38:41], v[130:133], v[18:33]
	s_nop 9
	s_nop 0
	s_nop 0
	v_max_f32_e32 v34, v3, v2
	v_max3_f32 v34, v34, v4, v5
	v_max3_f32 v34, v34, v6, v7
	v_max3_f32 v34, v34, v8, v9
	v_max3_f32 v34, v34, v10, v11
	v_max3_f32 v34, v34, v12, v13
	v_max3_f32 v34, v34, v14, v15
	v_max3_f32 v34, v34, v16, v17
	v_max3_f32 v34, v34, v18, v19
	v_max3_f32 v34, v34, v20, v21
	v_max3_f32 v34, v34, v22, v23
	v_max3_f32 v34, v34, v24, v25
	v_max3_f32 v34, v34, v26, v27
	v_max3_f32 v34, v34, v28, v29
	v_max3_f32 v34, v34, v30, v31
	v_max3_f32 v34, v34, v32, v33
	v_mov_b32_e32 v35, v34
	s_nop 1
	v_permlane32_swap_b32_e32 v34, v35
	s_nop 0
	s_nop 0
	v_max_f32_e32 v35, v35, v34
	v_sub_f32_e32 v2, v2, v35
	v_sub_f32_e32 v3, v3, v35
	v_exp_f32_e32 v2, v2
	v_sub_f32_e32 v4, v4, v35
	v_exp_f32_e32 v3, v3
	v_sub_f32_e32 v5, v5, v35
	v_exp_f32_e32 v4, v4
	v_sub_f32_e32 v6, v6, v35
	v_exp_f32_e32 v5, v5
	v_sub_f32_e32 v7, v7, v35
	v_exp_f32_e32 v6, v6
	v_add_f32_e32 v34, 0, v2
	v_sub_f32_e32 v8, v8, v35
	v_exp_f32_e32 v7, v7
	v_add_f32_e32 v34, v3, v34
	v_sub_f32_e32 v9, v9, v35
	v_exp_f32_e32 v8, v8
	v_add_f32_e32 v34, v4, v34
	v_sub_f32_e32 v10, v10, v35
	v_exp_f32_e32 v9, v9
	v_add_f32_e32 v34, v5, v34
	v_sub_f32_e32 v11, v11, v35
	v_exp_f32_e32 v10, v10
	v_add_f32_e32 v34, v6, v34
	v_sub_f32_e32 v12, v12, v35
	v_exp_f32_e32 v11, v11
	v_add_f32_e32 v34, v7, v34
	v_sub_f32_e32 v13, v13, v35
	v_exp_f32_e32 v12, v12
	v_add_f32_e32 v34, v8, v34
	v_sub_f32_e32 v14, v14, v35
	v_exp_f32_e32 v13, v13
	v_add_f32_e32 v34, v9, v34
	v_sub_f32_e32 v15, v15, v35
	v_exp_f32_e32 v14, v14
	v_add_f32_e32 v34, v10, v34
	v_sub_f32_e32 v16, v16, v35
	v_exp_f32_e32 v15, v15
	v_add_f32_e32 v34, v11, v34
	v_sub_f32_e32 v17, v17, v35
	v_exp_f32_e32 v16, v16
	v_add_f32_e32 v34, v12, v34
	v_sub_f32_e32 v18, v18, v35
	v_exp_f32_e32 v17, v17
	v_add_f32_e32 v34, v13, v34
	v_sub_f32_e32 v19, v19, v35
	v_exp_f32_e32 v18, v18
	v_add_f32_e32 v34, v14, v34
	v_sub_f32_e32 v20, v20, v35
	v_exp_f32_e32 v19, v19
	v_add_f32_e32 v34, v15, v34
	v_sub_f32_e32 v21, v21, v35
	v_exp_f32_e32 v20, v20
	v_add_f32_e32 v34, v16, v34
	v_sub_f32_e32 v22, v22, v35
	v_exp_f32_e32 v21, v21
	v_add_f32_e32 v34, v17, v34
	v_sub_f32_e32 v23, v23, v35
	v_exp_f32_e32 v22, v22
	v_add_f32_e32 v34, v18, v34
	v_sub_f32_e32 v24, v24, v35
	v_exp_f32_e32 v23, v23
	v_add_f32_e32 v34, v19, v34
	v_sub_f32_e32 v25, v25, v35
	v_exp_f32_e32 v24, v24
	v_add_f32_e32 v34, v20, v34
	v_sub_f32_e32 v26, v26, v35
	v_exp_f32_e32 v25, v25
	v_add_f32_e32 v34, v21, v34
	v_sub_f32_e32 v27, v27, v35
	v_exp_f32_e32 v26, v26
	v_add_f32_e32 v34, v22, v34
	v_sub_f32_e32 v28, v28, v35
	v_exp_f32_e32 v27, v27
	v_add_f32_e32 v34, v23, v34
	v_sub_f32_e32 v29, v29, v35
	v_exp_f32_e32 v28, v28
	v_add_f32_e32 v34, v24, v34
	v_sub_f32_e32 v30, v30, v35
	v_exp_f32_e32 v29, v29
	v_add_f32_e32 v34, v25, v34
	v_sub_f32_e32 v31, v31, v35
	v_exp_f32_e32 v30, v30
	v_add_f32_e32 v34, v26, v34
	v_sub_f32_e32 v32, v32, v35
	v_exp_f32_e32 v31, v31
	v_add_f32_e32 v34, v27, v34
	v_sub_f32_e32 v33, v33, v35
	v_exp_f32_e32 v32, v32
	v_add_f32_e32 v34, v28, v34
	v_exp_f32_e32 v33, v33
	v_add_f32_e32 v34, v29, v34
	v_add_f32_e32 v34, v30, v34
	v_add_f32_e32 v34, v31, v34
	v_add_f32_e32 v34, v32, v34
	v_add_f32_e32 v34, v33, v34
	v_mov_b32_e32 v36, v34
	s_nop 1
	v_permlane32_swap_b32_e32 v34, v36
	v_add_f32_e32 v34, v34, v36
	v_pk_add_f32 v[202:203], v[34:35], 0 op_sel_hi:[1,0]
	v_cvt_pk_bf16_f32 v72, v2, v3
	v_cvt_pk_bf16_f32 v73, v4, v5
	v_cvt_pk_bf16_f32 v74, v6, v7
	v_cvt_pk_bf16_f32 v75, v8, v9
	v_cvt_pk_bf16_f32 v76, v10, v11
	s_nop 0
	v_xor_b32_e32 v66, 0x80000000, v203
	v_cvt_pk_bf16_f32 v77, v12, v13
	v_cvt_pk_bf16_f32 v78, v14, v15
	v_cvt_pk_bf16_f32 v79, v16, v17
	v_cvt_pk_bf16_f32 v80, v18, v19
	v_cvt_pk_bf16_f32 v81, v20, v21
	v_cvt_pk_bf16_f32 v82, v22, v23
	v_cvt_pk_bf16_f32 v83, v24, v25
	v_cvt_pk_bf16_f32 v84, v26, v27
	v_cvt_pk_bf16_f32 v85, v28, v29
	v_cvt_pk_bf16_f32 v86, v30, v31
	v_cvt_pk_bf16_f32 v87, v32, v33
	ds_read_b64_tr_b16 v[2:3], v237 offset:0
	ds_read_b64_tr_b16 v[4:5], v237 offset:0x800
	ds_read_b64_tr_b16 v[18:19], v237 offset:0x1000
	ds_read_b64_tr_b16 v[20:21], v237 offset:0x1800
	ds_read_b64_tr_b16 v[22:23], v237 offset:0x2000
	ds_read_b64_tr_b16 v[24:25], v237 offset:0x2800
	ds_read_b64_tr_b16 v[26:27], v237 offset:0x3000
	ds_read_b64_tr_b16 v[28:29], v237 offset:0x3800
	s_waitcnt lgkmcnt(0)
	s_nop 0
	v_mfma_f32_32x32x16_bf16 v[2:17], v[72:75], v[2:5], 0
	v_mfma_f32_32x32x16_bf16 v[2:17], v[76:79], v[18:21], v[2:17]
	ds_read_b64_tr_b16 v[18:19], v237 offset:0x200
	ds_read_b64_tr_b16 v[20:21], v237 offset:0xa00
	ds_read_b64_tr_b16 v[34:35], v237 offset:0x1200
	ds_read_b64_tr_b16 v[36:37], v237 offset:0x1a00
	ds_read_b64_tr_b16 v[38:39], v237 offset:0x2200
	ds_read_b64_tr_b16 v[40:41], v237 offset:0x2a00
	ds_read_b64_tr_b16 v[42:43], v237 offset:0x3200
	v_mfma_f32_32x32x16_bf16 v[2:17], v[80:83], v[22:25], v[2:17]
	ds_read_b64_tr_b16 v[44:45], v237 offset:0x3a00
	s_waitcnt lgkmcnt(0)
	v_mfma_f32_32x32x16_bf16 v[2:17], v[84:87], v[26:29], v[2:17]
	v_mfma_f32_32x32x16_bf16 v[18:33], v[72:75], v[18:21], 0
	v_mfma_f32_32x32x16_bf16 v[18:33], v[76:79], v[34:37], v[18:33]
	ds_read_b64_tr_b16 v[34:35], v237 offset:0x400
	ds_read_b64_tr_b16 v[36:37], v237 offset:0xc00
	ds_read_b64_tr_b16 v[88:89], v237 offset:0x1400
	ds_read_b64_tr_b16 v[90:91], v237 offset:0x1c00
	ds_read_b64_tr_b16 v[92:93], v237 offset:0x2400
	ds_read_b64_tr_b16 v[94:95], v237 offset:0x2c00
	ds_read_b64_tr_b16 v[96:97], v237 offset:0x3400
	v_mfma_f32_32x32x16_bf16 v[18:33], v[80:83], v[38:41], v[18:33]
	ds_read_b64_tr_b16 v[98:99], v237 offset:0x3c00
	s_waitcnt lgkmcnt(0)
	v_mfma_f32_32x32x16_bf16 v[18:33], v[84:87], v[42:45], v[18:33]
	v_mfma_f32_32x32x16_bf16 v[34:49], v[72:75], v[34:37], 0
	v_mfma_f32_32x32x16_bf16 v[34:49], v[76:79], v[88:91], v[34:49]
	ds_read_b64_tr_b16 v[88:89], v237 offset:0x600
	ds_read_b64_tr_b16 v[90:91], v237 offset:0xe00
	v_mfma_f32_32x32x16_bf16 v[34:49], v[80:83], v[92:95], v[34:49]
	ds_read_b64_tr_b16 v[92:93], v237 offset:0x1600
	ds_read_b64_tr_b16 v[94:95], v237 offset:0x1e00
	v_mfma_f32_32x32x16_bf16 v[34:49], v[84:87], v[96:99], v[34:49]
	ds_read_b64_tr_b16 v[96:97], v237 offset:0x2600
	ds_read_b64_tr_b16 v[98:99], v237 offset:0x2e00
	ds_read_b64_tr_b16 v[100:101], v237 offset:0x3600
	ds_read_b64_tr_b16 v[102:103], v237 offset:0x3e00
	s_waitcnt lgkmcnt(0)
	s_waitcnt vmcnt(1)
	ds_write_b128 v62, v[54:57] offset:16384
	s_waitcnt vmcnt(0)
	ds_write_b128 v63, v[58:61] offset:16384
	ds_write_b128 v64, v[50:53] offset:49152
	v_mfma_f32_32x32x16_bf16 v[50:65], v[72:75], v[88:91], 0
	ds_write_b128 v67, v[68:71] offset:49152
	s_addk_i32 s10, 0x80
	s_mov_b32 s14, 0
	s_movk_i32 s15, 0x4000
	v_mov_b32_e32 v67, v66
	v_mov_b32_e32 v68, v66
	v_mov_b32_e32 v69, v66
	v_mfma_f32_32x32x16_bf16 v[50:65], v[76:79], v[92:95], v[50:65]
	v_mov_b32_e32 v70, v66
	v_mov_b32_e32 v71, v66
	v_mov_b32_e32 v72, v66
	v_mov_b32_e32 v73, v66
	v_mov_b32_e32 v74, v66
	v_mov_b32_e32 v75, v66
	v_mov_b32_e32 v76, v66
	v_mfma_f32_32x32x16_bf16 v[50:65], v[80:83], v[96:99], v[50:65]
	v_mov_b32_e32 v77, v66
	v_mov_b32_e32 v78, v66
	v_mov_b32_e32 v79, v66
	v_mov_b32_e32 v80, v66
	v_mov_b32_e32 v81, v66
	s_waitcnt lgkmcnt(0)
	s_barrier
	v_mfma_f32_32x32x16_bf16 v[50:65], v[84:87], v[100:103], v[50:65]
	s_and_b32 s24, s22, 7
	s_lshl_b32 s24, s24, 6
	s_and_b32 s24, s24, 0x100
	s_mul_i32 s25, s10, 0x1400
	s_add_u32 s24, s24, s25
	s_add_u32 s24, s18, s24
	s_addc_u32 s25, s19, 0
	v_readlane_b32 s26, v254, 10
	s_nop 3
	s_lshl_b32 s26, s26, 5
	s_add_i32 s26, s26, 16
	v_add_u32_e32 v162, v227, v228
	v_add_u32_e32 v163, v227, v229
	v_add_u32_e32 v164, v227, v230
	v_add_u32_e32 v165, v227, v231
	v_add_u32_e32 v166, v227, v232
	v_add_u32_e32 v167, v227, v233
	v_add_u32_e32 v168, v227, v234
	v_add_u32_e32 v169, v227, v235
	s_nop 0
	s_nop 0
	s_nop 0
	s_add_i32 m0, s26, 0x8000
	s_nop 0
	global_load_lds_dwordx4 v252, s[24:25]
	s_add_i32 m0, s26, 0x8400
	s_nop 0
	global_load_lds_dwordx4 v253, s[24:25]
	s_add_u32 s24, s24, 0x50000
	s_addc_u32 s25, s25, 0

.Lpp_a_sJ:
	s_nop 1
	s_nop 0
	s_nop 0
	v_max_f32_e32 v82, v115, v114
	v_max3_f32 v82, v82, v116, v117
	v_max3_f32 v82, v82, v118, v119
	v_max3_f32 v82, v82, v120, v121
	v_max3_f32 v82, v82, v122, v123
	v_max3_f32 v82, v82, v124, v125
	v_max3_f32 v82, v82, v126, v127
	v_max3_f32 v82, v82, v128, v129
	v_max3_f32 v82, v82, v98, v99
	v_max3_f32 v82, v82, v100, v101
	v_max3_f32 v82, v82, v102, v103
	v_max3_f32 v82, v82, v104, v105
	v_max3_f32 v82, v82, v106, v107
	v_max3_f32 v82, v82, v108, v109
	v_max3_f32 v82, v82, v110, v111
	v_max3_f32 v82, v82, v112, v113
	v_mov_b32_e32 v83, v82
	s_nop 1
	v_permlane32_swap_b32_e32 v82, v83
	s_nop 0
	s_nop 0
	v_max_f32_e32 v82, v83, v82
	v_cmp_ge_f32_e32 vcc, s64, v82
	s_cmp_eq_u64 vcc, exec
	s_cbranch_scc0 .Lgu_a294
	v_mov_b32_e32 v195, 1.0

.LBB0_295:
	s_nop 0
	s_nop 0
	s_nop 0
	s_nop 0
	s_nop 0
	s_nop 0
	s_nop 0
	s_nop 0
	s_nop 0
	s_nop 0
	s_nop 0
	s_nop 0
	s_nop 0
	s_nop 0
	v_mov_b64_e32 v[82:83], v[66:67]
	v_mov_b64_e32 v[84:85], v[68:69]
	v_mov_b64_e32 v[86:87], v[70:71]
	v_mov_b64_e32 v[88:89], v[72:73]
	v_mov_b64_e32 v[90:91], v[74:75]
	v_mov_b64_e32 v[92:93], v[76:77]
	v_mov_b64_e32 v[94:95], v[78:79]
	v_mov_b64_e32 v[96:97], v[80:81]
	s_lshl_b32 s10, s14, 14
	s_addk_i32 s10, 0x4000
	s_and_b32 s12, s10, 0x4000
	v_add_u32_e32 v102, s12, v227
	v_add_u32_e32 v103, v102, v228
	ds_read_b128 v[98:101], v103 offset:32768
	s_waitcnt lgkmcnt(0)
	v_mfma_f32_32x32x16_bf16 v[66:81], v[98:101], v[134:137], v[82:97]
	ds_read_b128 v[98:101], v103 offset:40960
	v_add_u32_e32 v103, v102, v229
	s_waitcnt lgkmcnt(0)
	v_mfma_f32_32x32x16_bf16 v[82:97], v[98:101], v[134:137], v[82:97]
	ds_read_b128 v[98:101], v103 offset:32768
	s_waitcnt lgkmcnt(0)
	v_mfma_f32_32x32x16_bf16 v[66:81], v[98:101], v[142:145], v[66:81]
	ds_read_b128 v[98:101], v103 offset:40960
	v_add_u32_e32 v103, v102, v230
	s_waitcnt lgkmcnt(0)
	v_mfma_f32_32x32x16_bf16 v[82:97], v[98:101], v[142:145], v[82:97]
	ds_read_b128 v[98:101], v103 offset:32768
	s_waitcnt lgkmcnt(0)
	v_mfma_f32_32x32x16_bf16 v[66:81], v[98:101], v[146:149], v[66:81]
	ds_read_b128 v[98:101], v103 offset:40960
	v_add_u32_e32 v103, v102, v231
	s_waitcnt lgkmcnt(0)
	v_mfma_f32_32x32x16_bf16 v[82:97], v[98:101], v[146:149], v[82:97]
	ds_read_b128 v[98:101], v103 offset:32768
	s_waitcnt lgkmcnt(0)
	v_mfma_f32_32x32x16_bf16 v[66:81], v[98:101], v[150:153], v[66:81]
	ds_read_b128 v[98:101], v103 offset:40960
	v_add_u32_e32 v103, v102, v232
	s_waitcnt lgkmcnt(0)
	v_mfma_f32_32x32x16_bf16 v[82:97], v[98:101], v[150:153], v[82:97]
	ds_read_b128 v[98:101], v103 offset:32768
	s_waitcnt lgkmcnt(0)
	v_mfma_f32_32x32x16_bf16 v[66:81], v[98:101], v[154:157], v[66:81]
	ds_read_b128 v[98:101], v103 offset:40960
	v_add_u32_e32 v103, v102, v233
	s_waitcnt lgkmcnt(0)
	v_mfma_f32_32x32x16_bf16 v[82:97], v[98:101], v[154:157], v[82:97]
	ds_read_b128 v[98:101], v103 offset:32768
	s_waitcnt lgkmcnt(0)
	v_mfma_f32_32x32x16_bf16 v[66:81], v[98:101], v[158:161], v[66:81]
	ds_read_b128 v[98:101], v103 offset:40960
	v_add_u32_e32 v103, v102, v234
	v_add_u32_e32 v102, v102, v235
	s_waitcnt lgkmcnt(0)
	v_mfma_f32_32x32x16_bf16 v[82:97], v[98:101], v[158:161], v[82:97]
	ds_read_b128 v[98:101], v103 offset:32768
	s_waitcnt lgkmcnt(0)
	v_mfma_f32_32x32x16_bf16 v[66:81], v[98:101], v[138:141], v[66:81]
	ds_read_b128 v[98:101], v102 offset:32768
	s_waitcnt lgkmcnt(0)
	v_mfma_f32_32x32x16_bf16 v[66:81], v[98:101], v[130:133], v[66:81]
	ds_read_b128 v[98:101], v103 offset:40960
	ds_read_b128 v[102:105], v102 offset:40960
	s_waitcnt lgkmcnt(1)
	v_mfma_f32_32x32x16_bf16 v[82:97], v[98:101], v[138:141], v[82:97]
	s_nop 7
	v_max_f32_e32 v106, v67, v67
	v_max_f32_e32 v107, v66, v66
	v_max_f32_e32 v106, v107, v106
	v_max3_f32 v98, v106, v68, v69
	v_max3_f32 v98, v98, v70, v71
	v_max3_f32 v98, v98, v72, v73
	v_max3_f32 v98, v98, v74, v75
	s_waitcnt lgkmcnt(0)
	v_mfma_f32_32x32x16_bf16 v[82:97], v[102:105], v[130:133], v[82:97]
	v_max3_f32 v98, v98, v76, v77
	v_max3_f32 v98, v98, v78, v79
	v_max3_f32 v98, v98, v80, v81
	s_nop 8
	v_max3_f32 v98, v98, v82, v83
	v_max3_f32 v98, v98, v84, v85
	v_max3_f32 v98, v98, v86, v87
	v_max3_f32 v98, v98, v88, v89
	v_max3_f32 v98, v98, v90, v91
	v_max3_f32 v98, v98, v92, v93
	v_max3_f32 v98, v98, v94, v95
	v_max3_f32 v98, v98, v96, v97
	v_mov_b32_e32 v99, v98
	s_nop 1
	v_permlane32_swap_b32_e32 v98, v99
	s_nop 0
	s_nop 0
	v_max_f32_e32 v99, v99, v98
	v_cmp_ge_f32_e32 vcc, s64, v99
	s_cmp_eq_u64 vcc, exec
	v_mov_b32_e32 v98, 1.0
	s_cbranch_scc0 .LBB0_307
